# K-loops: the wait state between each M0 write and its LDS-DMA load is filled by one of the segment's LDS fragment reads instead of s_nop (42 sites)
# speedup vs baseline: 1.0061x; 1.0061x over previous
; #define PG8_STAGE(bufoff, gbase) do { _Pragma("unroll") for (int _i = 0; _i < 2; ++_i) \
;     __builtin_amdgcn_global_load_lds((const unsigned*)((const char*)(gbase) + voff[_i]), (LAS unsigned*)(lds + (bufoff) + ldsw + _i * 8192), 16, 0, 0); } while (0)
; #define PG8_LDA(dst, b, h) do { _Pragma("unroll") for (int m = 0; m < 4; ++m) _Pragma("unroll") for (int k = 0; k < 2; ++k) dst[m][k] = *(const LAS bf16x8*)(lds + PG8_SA(b, h) + aoff + m * 2048 + k * 1024); } while (0)
; #define PG8_LDB(dst, b, h) do { _Pragma("unroll") for (int n = 0; n < 2; ++n) _Pragma("unroll") for (int k = 0; k < 2; ++k) dst[n][k] = *(const LAS bf16x8*)(lds + PG8_SB(b, h) + boff + n * 2048 + k * 1024); } while (0)
; #define PG8_WAIT_V(n) asm volatile("s_waitcnt vmcnt(" #n ")" ::: "memory")
; #define PG8_WAIT_L(n) asm volatile("s_waitcnt lgkmcnt(" #n ")" ::: "memory")
; #define PG8_BAR __builtin_amdgcn_s_barrier()
; #define PG8_SCHED __builtin_amdgcn_sched_barrier(0)
; template <int EPI, bool ALIGN_EPI = true, bool SP2 = true>
; DI void gemm8_phase(const GemmArgs& g, char* lds_) {
;     ...
;         PG8_LDB(B0, 0, 0); PG8_LDB(B1, 0, 1); PG8_SCHED; PG8_LDA(At, 0, 0); PG8_STAGE(PG8_SA(1, 1), a1 + hstep);
;         if (relax) PG8_WAIT_V(24); else PG8_WAIT_V(8);
;         PG8_WAIT_L(0); PG8_BAR; PG8_MMA(0, 0, At, B0); PG8_MMA(0, 1, At, B1); PG8_BAR; PG8_SCHED;
;         PG8_LDA(At, 0, 1); PG8_STAGE(PG8_SB(0, 0), b2); PG8_STAGE(PG8_SB(0, 1), b2 + hstep); PG8_STAGE(PG8_SA(0, 0), a2);
;         if (relax) PG8_WAIT_V(24); else PG8_WAIT_V(8);
;         PG8_WAIT_L(0); PG8_BAR; PG8_MMA(1, 0, At, B0); PG8_MMA(1, 1, At, B1); PG8_BAR; PG8_SCHED;
;         PG8_LDB(B0, 1, 0); PG8_LDB(B1, 1, 1); PG8_SCHED; PG8_LDA(At, 1, 0); PG8_STAGE(PG8_SA(0, 1), a2 + hstep);
.LBB0_292:
	ds_read_b128 v[158:161], v141
	ds_read_b128 v[168:171], v142
	ds_read_b128 v[192:195], v143
	ds_read_b128 v[196:199], v144
	ds_read_b128 v[200:203], v145
	ds_read_b128 v[204:207], v146
	ds_read_b128 v[208:211], v147
	ds_read_b128 v[212:215], v148
	s_add_u32 s84, s34, 0x100
	s_addc_u32 s85, s35, 0
	s_cmp_eq_u32 vcc_lo, 12
	s_cselect_b32 s91, s45, s85
	s_cselect_b32 s90, s44, s84
	s_cselect_b32 s87, s22, s43
	s_cselect_b32 s86, s23, s41
	s_mov_b32 m0, s17
	ds_read_b128 v[216:219], v139
	ds_read_b128 v[220:223], v139 offset:1024
	ds_read_b128 v[224:227], v139 offset:2048
	ds_read_b128 v[228:231], v139 offset:3072
	ds_read_b128 v[232:235], v139 offset:4096
	ds_read_b128 v[236:239], v139 offset:5120
	ds_read_b128 v[240:243], v139 offset:6144
	global_load_lds_dwordx4 v132, s[34:35]
	s_mov_b32 m0, s16
	ds_read_b128 v[244:247], v139 offset:7168
	global_load_lds_dwordx4 v134, s[34:35]
	s_waitcnt vmcnt(8)
	s_waitcnt lgkmcnt(0)
	s_barrier
	s_setprio 1
	s_waitcnt lgkmcnt(0)
	v_mfma_f32_16x16x32_bf16 v[122:125], v[158:161], v[216:219], v[122:125]
	v_mfma_f32_16x16x32_bf16 v[126:129], v[192:195], v[216:219], v[126:129]
	v_mfma_f32_16x16x32_bf16 v[114:117], v[158:161], v[224:227], v[114:117]
	v_mfma_f32_16x16x32_bf16 v[118:121], v[192:195], v[224:227], v[118:121]
	v_mfma_f32_16x16x32_bf16 v[106:109], v[158:161], v[232:235], v[106:109]
	v_mfma_f32_16x16x32_bf16 v[110:113], v[192:195], v[232:235], v[110:113]
	v_mfma_f32_16x16x32_bf16 v[98:101], v[158:161], v[240:243], v[98:101]
	v_mfma_f32_16x16x32_bf16 v[102:105], v[192:195], v[240:243], v[102:105]
	v_mfma_f32_16x16x32_bf16 v[122:125], v[168:171], v[220:223], v[122:125]
	v_mfma_f32_16x16x32_bf16 v[126:129], v[196:199], v[220:223], v[126:129]
	v_mfma_f32_16x16x32_bf16 v[114:117], v[168:171], v[228:231], v[114:117]
	v_mfma_f32_16x16x32_bf16 v[118:121], v[196:199], v[228:231], v[118:121]
	v_mfma_f32_16x16x32_bf16 v[106:109], v[168:171], v[236:239], v[106:109]
	v_mfma_f32_16x16x32_bf16 v[110:113], v[196:199], v[236:239], v[110:113]
	v_mfma_f32_16x16x32_bf16 v[98:101], v[168:171], v[244:247], v[98:101]
	v_mfma_f32_16x16x32_bf16 v[102:105], v[196:199], v[244:247], v[102:105]
	s_setprio 0
	s_setprio 1
	v_mfma_f32_16x16x32_bf16 v[90:93], v[200:203], v[216:219], v[90:93]
	v_mfma_f32_16x16x32_bf16 v[94:97], v[208:211], v[216:219], v[94:97]
	v_mfma_f32_16x16x32_bf16 v[82:85], v[200:203], v[224:227], v[82:85]
	v_mfma_f32_16x16x32_bf16 v[86:89], v[208:211], v[224:227], v[86:89]
	v_mfma_f32_16x16x32_bf16 v[74:77], v[200:203], v[232:235], v[74:77]
	v_mfma_f32_16x16x32_bf16 v[78:81], v[208:211], v[232:235], v[78:81]
	v_mfma_f32_16x16x32_bf16 v[66:69], v[200:203], v[240:243], v[66:69]
	v_mfma_f32_16x16x32_bf16 v[70:73], v[208:211], v[240:243], v[70:73]
	v_mfma_f32_16x16x32_bf16 v[90:93], v[204:207], v[220:223], v[90:93]
	v_mfma_f32_16x16x32_bf16 v[94:97], v[212:215], v[220:223], v[94:97]
	v_mfma_f32_16x16x32_bf16 v[82:85], v[204:207], v[228:231], v[82:85]
	v_mfma_f32_16x16x32_bf16 v[86:89], v[212:215], v[228:231], v[86:89]
	v_mfma_f32_16x16x32_bf16 v[74:77], v[204:207], v[236:239], v[74:77]
	v_mfma_f32_16x16x32_bf16 v[78:81], v[212:215], v[236:239], v[78:81]
	v_mfma_f32_16x16x32_bf16 v[66:69], v[204:207], v[244:247], v[66:69]
	v_mfma_f32_16x16x32_bf16 v[70:73], v[212:215], v[244:247], v[70:73]
	s_setprio 0
	s_barrier
	s_mov_b32 m0, s9
	s_add_u32 s24, s86, 0x40000
	ds_read_b128 v[216:219], v139 offset:16384
	ds_read_b128 v[220:223], v139 offset:17408
	ds_read_b128 v[224:227], v139 offset:18432
	ds_read_b128 v[228:231], v139 offset:19456
	global_load_lds_dwordx4 v0, s[86:87]
	s_mov_b32 m0, s10
	s_addc_u32 s25, s87, 0
	global_load_lds_dwordx4 v130, s[86:87]
	s_mov_b32 m0, s11
	ds_read_b128 v[244:247], v139 offset:23552
	global_load_lds_dwordx4 v0, s[24:25]
	s_mov_b32 m0, s28
	ds_read_b128 v[240:243], v139 offset:22528
	global_load_lds_dwordx4 v130, s[24:25]
	s_mov_b32 m0, s18
	ds_read_b128 v[236:239], v139 offset:21504
	global_load_lds_dwordx4 v0, s[90:91]
	s_mov_b32 m0, s50
	ds_read_b128 v[232:235], v139 offset:20480
	global_load_lds_dwordx4 v130, s[90:91]
	s_waitcnt vmcnt(8)
	s_waitcnt lgkmcnt(0)
	s_barrier
	s_setprio 1
	s_waitcnt lgkmcnt(0)
	v_mfma_f32_16x16x32_bf16 v[58:61], v[158:161], v[216:219], v[58:61]
	v_mfma_f32_16x16x32_bf16 v[62:65], v[192:195], v[216:219], v[62:65]
	v_mfma_f32_16x16x32_bf16 v[50:53], v[158:161], v[224:227], v[50:53]
	v_mfma_f32_16x16x32_bf16 v[54:57], v[192:195], v[224:227], v[54:57]
	v_mfma_f32_16x16x32_bf16 v[42:45], v[158:161], v[232:235], v[42:45]
	v_mfma_f32_16x16x32_bf16 v[46:49], v[192:195], v[232:235], v[46:49]
	v_mfma_f32_16x16x32_bf16 v[34:37], v[158:161], v[240:243], v[34:37]
	v_mfma_f32_16x16x32_bf16 v[38:41], v[192:195], v[240:243], v[38:41]
	v_mfma_f32_16x16x32_bf16 v[58:61], v[168:171], v[220:223], v[58:61]
	v_mfma_f32_16x16x32_bf16 v[62:65], v[196:199], v[220:223], v[62:65]
	v_mfma_f32_16x16x32_bf16 v[50:53], v[168:171], v[228:231], v[50:53]
	v_mfma_f32_16x16x32_bf16 v[54:57], v[196:199], v[228:231], v[54:57]
	v_mfma_f32_16x16x32_bf16 v[42:45], v[168:171], v[236:239], v[42:45]
	v_mfma_f32_16x16x32_bf16 v[46:49], v[196:199], v[236:239], v[46:49]
	v_mfma_f32_16x16x32_bf16 v[34:37], v[168:171], v[244:247], v[34:37]
	v_mfma_f32_16x16x32_bf16 v[38:41], v[196:199], v[244:247], v[38:41]
	s_setprio 0
	s_setprio 1
	v_mfma_f32_16x16x32_bf16 v[26:29], v[200:203], v[216:219], v[26:29]
	v_mfma_f32_16x16x32_bf16 v[30:33], v[208:211], v[216:219], v[30:33]
	v_mfma_f32_16x16x32_bf16 v[18:21], v[200:203], v[224:227], v[18:21]
	v_mfma_f32_16x16x32_bf16 v[22:25], v[208:211], v[224:227], v[22:25]
	v_mfma_f32_16x16x32_bf16 v[10:13], v[200:203], v[232:235], v[10:13]
	v_mfma_f32_16x16x32_bf16 v[14:17], v[208:211], v[232:235], v[14:17]
	v_mfma_f32_16x16x32_bf16 v[2:5], v[200:203], v[240:243], v[2:5]
	v_mfma_f32_16x16x32_bf16 v[6:9], v[208:211], v[240:243], v[6:9]
	v_mfma_f32_16x16x32_bf16 v[26:29], v[204:207], v[220:223], v[26:29]
	v_mfma_f32_16x16x32_bf16 v[30:33], v[212:215], v[220:223], v[30:33]
	v_mfma_f32_16x16x32_bf16 v[18:21], v[204:207], v[228:231], v[18:21]
	v_mfma_f32_16x16x32_bf16 v[22:25], v[212:215], v[228:231], v[22:25]
	v_mfma_f32_16x16x32_bf16 v[10:13], v[204:207], v[236:239], v[10:13]
	v_mfma_f32_16x16x32_bf16 v[14:17], v[212:215], v[236:239], v[14:17]
	v_mfma_f32_16x16x32_bf16 v[2:5], v[204:207], v[244:247], v[2:5]
	v_mfma_f32_16x16x32_bf16 v[6:9], v[212:215], v[244:247], v[6:9]
	s_setprio 0
	s_barrier
; #define PG8_STAGE(bufoff, gbase) do { _Pragma("unroll") for (int _i = 0; _i < 2; ++_i) \
;     __builtin_amdgcn_global_load_lds((const unsigned*)((const char*)(gbase) + voff[_i]), (LAS unsigned*)(lds + (bufoff) + ldsw + _i * 8192), 16, 0, 0); } while (0)
; #define PG8_LDA(dst, b, h) do { _Pragma("unroll") for (int m = 0; m < 4; ++m) _Pragma("unroll") for (int k = 0; k < 2; ++k) dst[m][k] = *(const LAS bf16x8*)(lds + PG8_SA(b, h) + aoff + m * 2048 + k * 1024); } while (0)
; #define PG8_LDB(dst, b, h) do { _Pragma("unroll") for (int n = 0; n < 2; ++n) _Pragma("unroll") for (int k = 0; k < 2; ++k) dst[n][k] = *(const LAS bf16x8*)(lds + PG8_SB(b, h) + boff + n * 2048 + k * 1024); } while (0)
; #define PG8_WAIT_V(n) asm volatile("s_waitcnt vmcnt(" #n ")" ::: "memory")
; #define PG8_WAIT_L(n) asm volatile("s_waitcnt lgkmcnt(" #n ")" ::: "memory")
; #define PG8_BAR __builtin_amdgcn_s_barrier()
; #define PG8_SCHED __builtin_amdgcn_sched_barrier(0)
; template <int EPI, bool ALIGN_EPI = true, bool SP2 = true>
; DI void gemm8_phase(const GemmArgs& g, char* lds_) {
;     ...
;         PG8_LDB(B0, 1, 0); PG8_LDB(B1, 1, 1); PG8_SCHED; PG8_LDA(At, 1, 0); PG8_STAGE(PG8_SA(0, 1), a2 + hstep);
;         PG8_WAIT_V(8); PG8_WAIT_L(0); PG8_BAR; PG8_MMA(0, 0, At, B0); PG8_MMA(0, 1, At, B1); PG8_BAR; PG8_SCHED;
;         PG8_LDA(At, 1, 1); PG8_STAGE(PG8_SB(1, 0), b3); PG8_STAGE(PG8_SB(1, 1), b3 + hstep); PG8_STAGE(PG8_SA(1, 0), a3);
;         PG8_WAIT_V(8); PG8_WAIT_L(0); PG8_BAR; PG8_MMA(1, 0, At, B0); PG8_MMA(1, 1, At, B1); PG8_BAR; PG8_SCHED;
	ds_read_b128 v[158:161], v149
	ds_read_b128 v[168:171], v150
	ds_read_b128 v[192:195], v151
	ds_read_b128 v[196:199], v152
	ds_read_b128 v[200:203], v153
	ds_read_b128 v[204:207], v154
	ds_read_b128 v[208:211], v155
	ds_read_b128 v[212:215], v156
	s_add_u32 s24, s90, 0x40000
	s_addc_u32 s25, s91, 0
	s_mov_b32 m0, s51
	ds_read_b128 v[216:219], v139 offset:32768
	ds_read_b128 v[220:223], v139 offset:33792
	ds_read_b128 v[224:227], v139 offset:34816
	ds_read_b128 v[228:231], v139 offset:35840
	ds_read_b128 v[232:235], v139 offset:36864
	ds_read_b128 v[236:239], v139 offset:37888
	ds_read_b128 v[240:243], v139 offset:38912
	global_load_lds_dwordx4 v0, s[24:25]
	s_mov_b32 m0, s57
	ds_read_b128 v[244:247], v139 offset:39936
	global_load_lds_dwordx4 v130, s[24:25]
	s_waitcnt vmcnt(8)
	s_waitcnt lgkmcnt(0)
	s_barrier
	s_setprio 1
	s_waitcnt lgkmcnt(0)
	v_mfma_f32_16x16x32_bf16 v[122:125], v[158:161], v[216:219], v[122:125]
	v_mfma_f32_16x16x32_bf16 v[126:129], v[192:195], v[216:219], v[126:129]
	v_mfma_f32_16x16x32_bf16 v[114:117], v[158:161], v[224:227], v[114:117]
	v_mfma_f32_16x16x32_bf16 v[118:121], v[192:195], v[224:227], v[118:121]
	v_mfma_f32_16x16x32_bf16 v[106:109], v[158:161], v[232:235], v[106:109]
	v_mfma_f32_16x16x32_bf16 v[110:113], v[192:195], v[232:235], v[110:113]
	v_mfma_f32_16x16x32_bf16 v[98:101], v[158:161], v[240:243], v[98:101]
	v_mfma_f32_16x16x32_bf16 v[102:105], v[192:195], v[240:243], v[102:105]
	v_mfma_f32_16x16x32_bf16 v[122:125], v[168:171], v[220:223], v[122:125]
	v_mfma_f32_16x16x32_bf16 v[126:129], v[196:199], v[220:223], v[126:129]
	v_mfma_f32_16x16x32_bf16 v[114:117], v[168:171], v[228:231], v[114:117]
	v_mfma_f32_16x16x32_bf16 v[118:121], v[196:199], v[228:231], v[118:121]
	v_mfma_f32_16x16x32_bf16 v[106:109], v[168:171], v[236:239], v[106:109]
	v_mfma_f32_16x16x32_bf16 v[110:113], v[196:199], v[236:239], v[110:113]
	v_mfma_f32_16x16x32_bf16 v[98:101], v[168:171], v[244:247], v[98:101]
	v_mfma_f32_16x16x32_bf16 v[102:105], v[196:199], v[244:247], v[102:105]
	s_setprio 0
	s_setprio 1
	v_mfma_f32_16x16x32_bf16 v[90:93], v[200:203], v[216:219], v[90:93]
	v_mfma_f32_16x16x32_bf16 v[94:97], v[208:211], v[216:219], v[94:97]
	v_mfma_f32_16x16x32_bf16 v[82:85], v[200:203], v[224:227], v[82:85]
	v_mfma_f32_16x16x32_bf16 v[86:89], v[208:211], v[224:227], v[86:89]
	v_mfma_f32_16x16x32_bf16 v[74:77], v[200:203], v[232:235], v[74:77]
	v_mfma_f32_16x16x32_bf16 v[78:81], v[208:211], v[232:235], v[78:81]
	v_mfma_f32_16x16x32_bf16 v[66:69], v[200:203], v[240:243], v[66:69]
	v_mfma_f32_16x16x32_bf16 v[70:73], v[208:211], v[240:243], v[70:73]
	v_mfma_f32_16x16x32_bf16 v[90:93], v[204:207], v[220:223], v[90:93]
	v_mfma_f32_16x16x32_bf16 v[94:97], v[212:215], v[220:223], v[94:97]
	v_mfma_f32_16x16x32_bf16 v[82:85], v[204:207], v[228:231], v[82:85]
	v_mfma_f32_16x16x32_bf16 v[86:89], v[212:215], v[228:231], v[86:89]
	v_mfma_f32_16x16x32_bf16 v[74:77], v[204:207], v[236:239], v[74:77]
	v_mfma_f32_16x16x32_bf16 v[78:81], v[212:215], v[236:239], v[78:81]
	v_mfma_f32_16x16x32_bf16 v[66:69], v[204:207], v[244:247], v[66:69]
	v_mfma_f32_16x16x32_bf16 v[70:73], v[212:215], v[244:247], v[70:73]
	s_setprio 0
	s_barrier
	s_mov_b32 m0, s69
	s_add_u32 s24, s86, 0x40080
	ds_read_b128 v[216:219], v139 offset:49152
	ds_read_b128 v[220:223], v139 offset:50176
	ds_read_b128 v[224:227], v139 offset:51200
	ds_read_b128 v[228:231], v139 offset:52224
	global_load_lds_dwordx4 v164, s[86:87]
	s_mov_b32 m0, s8
	s_addc_u32 s25, s87, 0
	global_load_lds_dwordx4 v165, s[86:87]
	s_mov_b32 m0, s15
	ds_read_b128 v[244:247], v139 offset:56320
	global_load_lds_dwordx4 v0, s[24:25]
	s_mov_b32 m0, s14
	ds_read_b128 v[240:243], v139 offset:55296
	global_load_lds_dwordx4 v130, s[24:25]
	s_mov_b32 m0, s13
	ds_read_b128 v[236:239], v139 offset:54272
	global_load_lds_dwordx4 v164, s[90:91]
	s_mov_b32 m0, s12
	ds_read_b128 v[232:235], v139 offset:53248
	global_load_lds_dwordx4 v165, s[90:91]
	s_waitcnt vmcnt(8)
	s_waitcnt lgkmcnt(0)
	s_barrier
	s_setprio 1
	s_waitcnt lgkmcnt(0)
	v_mfma_f32_16x16x32_bf16 v[58:61], v[158:161], v[216:219], v[58:61]
	v_mfma_f32_16x16x32_bf16 v[62:65], v[192:195], v[216:219], v[62:65]
	v_mfma_f32_16x16x32_bf16 v[50:53], v[158:161], v[224:227], v[50:53]
	v_mfma_f32_16x16x32_bf16 v[54:57], v[192:195], v[224:227], v[54:57]
	v_mfma_f32_16x16x32_bf16 v[42:45], v[158:161], v[232:235], v[42:45]
	v_mfma_f32_16x16x32_bf16 v[46:49], v[192:195], v[232:235], v[46:49]
	v_mfma_f32_16x16x32_bf16 v[34:37], v[158:161], v[240:243], v[34:37]
	v_mfma_f32_16x16x32_bf16 v[38:41], v[192:195], v[240:243], v[38:41]
	v_mfma_f32_16x16x32_bf16 v[58:61], v[168:171], v[220:223], v[58:61]
	v_mfma_f32_16x16x32_bf16 v[62:65], v[196:199], v[220:223], v[62:65]
	v_mfma_f32_16x16x32_bf16 v[50:53], v[168:171], v[228:231], v[50:53]
	v_mfma_f32_16x16x32_bf16 v[54:57], v[196:199], v[228:231], v[54:57]
	v_mfma_f32_16x16x32_bf16 v[42:45], v[168:171], v[236:239], v[42:45]
	v_mfma_f32_16x16x32_bf16 v[46:49], v[196:199], v[236:239], v[46:49]
	v_mfma_f32_16x16x32_bf16 v[34:37], v[168:171], v[244:247], v[34:37]
	v_mfma_f32_16x16x32_bf16 v[38:41], v[196:199], v[244:247], v[38:41]
	s_setprio 0
	s_setprio 1
	v_mfma_f32_16x16x32_bf16 v[26:29], v[200:203], v[216:219], v[26:29]
	v_mfma_f32_16x16x32_bf16 v[30:33], v[208:211], v[216:219], v[30:33]
	v_mfma_f32_16x16x32_bf16 v[18:21], v[200:203], v[224:227], v[18:21]
	v_mfma_f32_16x16x32_bf16 v[22:25], v[208:211], v[224:227], v[22:25]
	v_mfma_f32_16x16x32_bf16 v[10:13], v[200:203], v[232:235], v[10:13]
	v_mfma_f32_16x16x32_bf16 v[14:17], v[208:211], v[232:235], v[14:17]
	v_mfma_f32_16x16x32_bf16 v[2:5], v[200:203], v[240:243], v[2:5]
	v_mfma_f32_16x16x32_bf16 v[6:9], v[208:211], v[240:243], v[6:9]
	v_mfma_f32_16x16x32_bf16 v[26:29], v[204:207], v[220:223], v[26:29]
	v_mfma_f32_16x16x32_bf16 v[30:33], v[212:215], v[220:223], v[30:33]
	v_mfma_f32_16x16x32_bf16 v[18:21], v[204:207], v[228:231], v[18:21]
	v_mfma_f32_16x16x32_bf16 v[22:25], v[212:215], v[228:231], v[22:25]
	v_mfma_f32_16x16x32_bf16 v[10:13], v[204:207], v[236:239], v[10:13]
	v_mfma_f32_16x16x32_bf16 v[14:17], v[212:215], v[236:239], v[14:17]
	v_mfma_f32_16x16x32_bf16 v[2:5], v[204:207], v[244:247], v[2:5]
	v_mfma_f32_16x16x32_bf16 v[6:9], v[212:215], v[244:247], v[6:9]
	s_setprio 0
	s_barrier
	s_add_i32 vcc_lo, vcc_lo, 2
	s_add_u32 s41, s41, 0x100
	s_addc_u32 s43, s43, 0
	s_cmp_gt_u32 vcc_lo, 13
	s_mov_b64 s[34:35], s[84:85]
	s_cbranch_scc0 .LBB0_292
	s_and_b64 vcc, exec, s[38:39]
	s_cbranch_vccz .LBB0_295
	s_barrier

; #define PG8_STAGE(bufoff, gbase) do { _Pragma("unroll") for (int _i = 0; _i < 2; ++_i) \
;     __builtin_amdgcn_global_load_lds((const unsigned*)((const char*)(gbase) + voff[_i]), (LAS unsigned*)(lds + (bufoff) + ldsw + _i * 8192), 16, 0, 0); } while (0)
; #define PG8_LDA(dst, b, h) do { _Pragma("unroll") for (int m = 0; m < 4; ++m) _Pragma("unroll") for (int k = 0; k < 2; ++k) dst[m][k] = *(const LAS bf16x8*)(lds + PG8_SA(b, h) + aoff + m * 2048 + k * 1024); } while (0)
; #define PG8_LDB(dst, b, h) do { _Pragma("unroll") for (int n = 0; n < 2; ++n) _Pragma("unroll") for (int k = 0; k < 2; ++k) dst[n][k] = *(const LAS bf16x8*)(lds + PG8_SB(b, h) + boff + n * 2048 + k * 1024); } while (0)
; #define PG8_WAIT_V(n) asm volatile("s_waitcnt vmcnt(" #n ")" ::: "memory")
; #define PG8_WAIT_L(n) asm volatile("s_waitcnt lgkmcnt(" #n ")" ::: "memory")
; #define PG8_BAR __builtin_amdgcn_s_barrier()
; #define PG8_SCHED __builtin_amdgcn_sched_barrier(0)
; template <int EPI, bool ALIGN_EPI = true, bool SP2 = true>
; DI void gemm8_phase(const GemmArgs& g, char* lds_) {
;     ...
;         PG8_LDB(B0, 0, 0); PG8_LDB(B1, 0, 1); PG8_SCHED; PG8_LDA(At, 0, 0); PG8_STAGE(PG8_SA(1, 1), a1 + hstep);
;         if (relax) PG8_WAIT_V(24); else PG8_WAIT_V(8);
;         PG8_WAIT_L(0); PG8_BAR; PG8_MMA(0, 0, At, B0); PG8_MMA(0, 1, At, B1); PG8_BAR; PG8_SCHED;
;         PG8_LDA(At, 0, 1); PG8_STAGE(PG8_SB(0, 0), b2); PG8_STAGE(PG8_SB(0, 1), b2 + hstep); PG8_STAGE(PG8_SA(0, 0), a2);
;         if (relax) PG8_WAIT_V(24); else PG8_WAIT_V(8);
;         PG8_WAIT_L(0); PG8_BAR; PG8_MMA(1, 0, At, B0); PG8_MMA(1, 1, At, B1); PG8_BAR; PG8_SCHED;
;         PG8_LDB(B0, 1, 0); PG8_LDB(B1, 1, 1); PG8_SCHED; PG8_LDA(At, 1, 0); PG8_STAGE(PG8_SA(0, 1), a2 + hstep);
.LBB0_381:
	ds_read_b128 v[138:141], v172
	ds_read_b128 v[142:145], v172 offset:1024
	ds_read_b128 v[154:157], v172 offset:2048
	ds_read_b128 v[158:161], v172 offset:3072
	ds_read_b128 v[168:171], v172 offset:16384
	ds_read_b128 v[192:195], v172 offset:17408
	ds_read_b128 v[196:199], v172 offset:18432
	ds_read_b128 v[200:203], v172 offset:19456
	s_add_u32 s40, s34, 0x100
	s_addc_u32 s41, s35, 0
	s_cmp_eq_u32 vcc_lo, 12
	s_cselect_b32 s91, s49, s41
	s_cselect_b32 s90, s48, s40
	s_cselect_b32 s87, s45, s51
	s_cselect_b32 s86, s47, s50
	s_add_i32 m0, s9, 0xc000
	ds_read_b128 v[204:207], v150
	ds_read_b128 v[208:211], v150 offset:1024
	ds_read_b128 v[212:215], v150 offset:2048
	ds_read_b128 v[216:219], v150 offset:3072
	ds_read_b128 v[220:223], v150 offset:4096
	ds_read_b128 v[224:227], v150 offset:5120
	ds_read_b128 v[228:231], v150 offset:6144
	global_load_lds_dwordx4 v134, s[34:35]
	s_add_i32 m0, s9, 0xe000
	ds_read_b128 v[232:235], v150 offset:7168
	global_load_lds_dwordx4 v136, s[34:35]
	s_waitcnt vmcnt(8)
	s_waitcnt lgkmcnt(0)
	s_barrier
	s_setprio 1
	s_waitcnt lgkmcnt(0)
	v_mfma_f32_16x16x32_bf16 v[126:129], v[138:141], v[204:207], v[126:129]
	v_mfma_f32_16x16x32_bf16 v[122:125], v[154:157], v[204:207], v[122:125]
	v_mfma_f32_16x16x32_bf16 v[118:121], v[138:141], v[212:215], v[118:121]
	v_mfma_f32_16x16x32_bf16 v[114:117], v[154:157], v[212:215], v[114:117]
	v_mfma_f32_16x16x32_bf16 v[110:113], v[138:141], v[220:223], v[110:113]
	v_mfma_f32_16x16x32_bf16 v[106:109], v[154:157], v[220:223], v[106:109]
	v_mfma_f32_16x16x32_bf16 v[102:105], v[138:141], v[228:231], v[102:105]
	v_mfma_f32_16x16x32_bf16 v[98:101], v[154:157], v[228:231], v[98:101]
	v_mfma_f32_16x16x32_bf16 v[126:129], v[142:145], v[208:211], v[126:129]
	v_mfma_f32_16x16x32_bf16 v[122:125], v[158:161], v[208:211], v[122:125]
	v_mfma_f32_16x16x32_bf16 v[118:121], v[142:145], v[216:219], v[118:121]
	v_mfma_f32_16x16x32_bf16 v[114:117], v[158:161], v[216:219], v[114:117]
	v_mfma_f32_16x16x32_bf16 v[110:113], v[142:145], v[224:227], v[110:113]
	v_mfma_f32_16x16x32_bf16 v[106:109], v[158:161], v[224:227], v[106:109]
	v_mfma_f32_16x16x32_bf16 v[102:105], v[142:145], v[232:235], v[102:105]
	v_mfma_f32_16x16x32_bf16 v[98:101], v[158:161], v[232:235], v[98:101]
	s_setprio 0
	s_setprio 1
	v_mfma_f32_16x16x32_bf16 v[94:97], v[168:171], v[204:207], v[94:97]
	v_mfma_f32_16x16x32_bf16 v[90:93], v[196:199], v[204:207], v[90:93]
	v_mfma_f32_16x16x32_bf16 v[86:89], v[168:171], v[212:215], v[86:89]
	v_mfma_f32_16x16x32_bf16 v[82:85], v[196:199], v[212:215], v[82:85]
	v_mfma_f32_16x16x32_bf16 v[78:81], v[168:171], v[220:223], v[78:81]
	v_mfma_f32_16x16x32_bf16 v[74:77], v[196:199], v[220:223], v[74:77]
	v_mfma_f32_16x16x32_bf16 v[70:73], v[168:171], v[228:231], v[70:73]
	v_mfma_f32_16x16x32_bf16 v[66:69], v[196:199], v[228:231], v[66:69]
	v_mfma_f32_16x16x32_bf16 v[94:97], v[192:195], v[208:211], v[94:97]
	v_mfma_f32_16x16x32_bf16 v[90:93], v[200:203], v[208:211], v[90:93]
	v_mfma_f32_16x16x32_bf16 v[86:89], v[192:195], v[216:219], v[86:89]
	v_mfma_f32_16x16x32_bf16 v[82:85], v[200:203], v[216:219], v[82:85]
	v_mfma_f32_16x16x32_bf16 v[78:81], v[192:195], v[224:227], v[78:81]
	v_mfma_f32_16x16x32_bf16 v[74:77], v[200:203], v[224:227], v[74:77]
	v_mfma_f32_16x16x32_bf16 v[70:73], v[192:195], v[232:235], v[70:73]
	v_mfma_f32_16x16x32_bf16 v[66:69], v[200:203], v[232:235], v[66:69]
	s_setprio 0
	s_barrier
	s_mov_b32 m0, s10
	s_add_u32 s24, s86, 0x40000
	ds_read_b128 v[204:207], v150 offset:16384
	ds_read_b128 v[208:211], v150 offset:17408
	ds_read_b128 v[212:215], v150 offset:18432
	ds_read_b128 v[216:219], v150 offset:19456
	global_load_lds_dwordx4 v130, s[86:87]
	s_mov_b32 m0, s11
	s_addc_u32 s25, s87, 0
	global_load_lds_dwordx4 v132, s[86:87]
	s_mov_b32 m0, s12
	ds_read_b128 v[232:235], v150 offset:23552
	global_load_lds_dwordx4 v130, s[24:25]
	s_mov_b32 m0, s13
	ds_read_b128 v[228:231], v150 offset:22528
	global_load_lds_dwordx4 v132, s[24:25]
	s_mov_b32 m0, s9
	ds_read_b128 v[224:227], v150 offset:21504
	global_load_lds_dwordx4 v130, s[90:91]
	s_mov_b32 m0, s14
	ds_read_b128 v[220:223], v150 offset:20480
	global_load_lds_dwordx4 v132, s[90:91]
	s_waitcnt vmcnt(8)
	s_waitcnt lgkmcnt(0)
	s_barrier
	s_setprio 1
	s_waitcnt lgkmcnt(0)
	v_mfma_f32_16x16x32_bf16 v[62:65], v[138:141], v[204:207], v[62:65]
	v_mfma_f32_16x16x32_bf16 v[58:61], v[154:157], v[204:207], v[58:61]
	v_mfma_f32_16x16x32_bf16 v[54:57], v[138:141], v[212:215], v[54:57]
	v_mfma_f32_16x16x32_bf16 v[50:53], v[154:157], v[212:215], v[50:53]
	v_mfma_f32_16x16x32_bf16 v[46:49], v[138:141], v[220:223], v[46:49]
	v_mfma_f32_16x16x32_bf16 v[42:45], v[154:157], v[220:223], v[42:45]
	v_mfma_f32_16x16x32_bf16 v[38:41], v[138:141], v[228:231], v[38:41]
	v_mfma_f32_16x16x32_bf16 v[34:37], v[154:157], v[228:231], v[34:37]
	v_mfma_f32_16x16x32_bf16 v[62:65], v[142:145], v[208:211], v[62:65]
	v_mfma_f32_16x16x32_bf16 v[58:61], v[158:161], v[208:211], v[58:61]
	v_mfma_f32_16x16x32_bf16 v[54:57], v[142:145], v[216:219], v[54:57]
	v_mfma_f32_16x16x32_bf16 v[50:53], v[158:161], v[216:219], v[50:53]
	v_mfma_f32_16x16x32_bf16 v[46:49], v[142:145], v[224:227], v[46:49]
	v_mfma_f32_16x16x32_bf16 v[42:45], v[158:161], v[224:227], v[42:45]
	v_mfma_f32_16x16x32_bf16 v[38:41], v[142:145], v[232:235], v[38:41]
	v_mfma_f32_16x16x32_bf16 v[34:37], v[158:161], v[232:235], v[34:37]
	s_setprio 0
	s_setprio 1
	v_mfma_f32_16x16x32_bf16 v[30:33], v[168:171], v[204:207], v[30:33]
	v_mfma_f32_16x16x32_bf16 v[26:29], v[196:199], v[204:207], v[26:29]
	v_mfma_f32_16x16x32_bf16 v[22:25], v[168:171], v[212:215], v[22:25]
	v_mfma_f32_16x16x32_bf16 v[18:21], v[196:199], v[212:215], v[18:21]
	v_mfma_f32_16x16x32_bf16 v[14:17], v[168:171], v[220:223], v[14:17]
	v_mfma_f32_16x16x32_bf16 v[10:13], v[196:199], v[220:223], v[10:13]
	v_mfma_f32_16x16x32_bf16 v[6:9], v[168:171], v[228:231], v[6:9]
	v_mfma_f32_16x16x32_bf16 v[2:5], v[196:199], v[228:231], v[2:5]
	v_mfma_f32_16x16x32_bf16 v[30:33], v[192:195], v[208:211], v[30:33]
	v_mfma_f32_16x16x32_bf16 v[26:29], v[200:203], v[208:211], v[26:29]
	v_mfma_f32_16x16x32_bf16 v[22:25], v[192:195], v[216:219], v[22:25]
	v_mfma_f32_16x16x32_bf16 v[18:21], v[200:203], v[216:219], v[18:21]
	v_mfma_f32_16x16x32_bf16 v[14:17], v[192:195], v[224:227], v[14:17]
	v_mfma_f32_16x16x32_bf16 v[10:13], v[200:203], v[224:227], v[10:13]
	v_mfma_f32_16x16x32_bf16 v[6:9], v[192:195], v[232:235], v[6:9]
	v_mfma_f32_16x16x32_bf16 v[2:5], v[200:203], v[232:235], v[2:5]
	s_setprio 0
	s_barrier
; #define PG8_STAGE(bufoff, gbase) do { _Pragma("unroll") for (int _i = 0; _i < 2; ++_i) \
;     __builtin_amdgcn_global_load_lds((const unsigned*)((const char*)(gbase) + voff[_i]), (LAS unsigned*)(lds + (bufoff) + ldsw + _i * 8192), 16, 0, 0); } while (0)
; #define PG8_LDA(dst, b, h) do { _Pragma("unroll") for (int m = 0; m < 4; ++m) _Pragma("unroll") for (int k = 0; k < 2; ++k) dst[m][k] = *(const LAS bf16x8*)(lds + PG8_SA(b, h) + aoff + m * 2048 + k * 1024); } while (0)
; #define PG8_LDB(dst, b, h) do { _Pragma("unroll") for (int n = 0; n < 2; ++n) _Pragma("unroll") for (int k = 0; k < 2; ++k) dst[n][k] = *(const LAS bf16x8*)(lds + PG8_SB(b, h) + boff + n * 2048 + k * 1024); } while (0)
; #define PG8_WAIT_V(n) asm volatile("s_waitcnt vmcnt(" #n ")" ::: "memory")
; #define PG8_WAIT_L(n) asm volatile("s_waitcnt lgkmcnt(" #n ")" ::: "memory")
; #define PG8_BAR __builtin_amdgcn_s_barrier()
; #define PG8_SCHED __builtin_amdgcn_sched_barrier(0)
; template <int EPI, bool ALIGN_EPI = true, bool SP2 = true>
; DI void gemm8_phase(const GemmArgs& g, char* lds_) {
;     ...
;         PG8_LDB(B0, 1, 0); PG8_LDB(B1, 1, 1); PG8_SCHED; PG8_LDA(At, 1, 0); PG8_STAGE(PG8_SA(0, 1), a2 + hstep);
;         PG8_WAIT_V(8); PG8_WAIT_L(0); PG8_BAR; PG8_MMA(0, 0, At, B0); PG8_MMA(0, 1, At, B1); PG8_BAR; PG8_SCHED;
;         PG8_LDA(At, 1, 1); PG8_STAGE(PG8_SB(1, 0), b3); PG8_STAGE(PG8_SB(1, 1), b3 + hstep); PG8_STAGE(PG8_SA(1, 0), a3);
;         PG8_WAIT_V(8); PG8_WAIT_L(0); PG8_BAR; PG8_MMA(1, 0, At, B0); PG8_MMA(1, 1, At, B1); PG8_BAR; PG8_SCHED;
	ds_read_b128 v[138:141], v172 offset:32768
	ds_read_b128 v[142:145], v172 offset:33792
	ds_read_b128 v[154:157], v172 offset:34816
	ds_read_b128 v[158:161], v172 offset:35840
	ds_read_b128 v[168:171], v172 offset:49152
	ds_read_b128 v[192:195], v172 offset:50176
	ds_read_b128 v[196:199], v172 offset:51200
	ds_read_b128 v[200:203], v172 offset:52224
	s_add_u32 s24, s90, 0x40000
	s_addc_u32 s25, s91, 0
	s_mov_b32 m0, s15
	ds_read_b128 v[204:207], v150 offset:32768
	ds_read_b128 v[208:211], v150 offset:33792
	ds_read_b128 v[212:215], v150 offset:34816
	ds_read_b128 v[216:219], v150 offset:35840
	ds_read_b128 v[220:223], v150 offset:36864
	ds_read_b128 v[224:227], v150 offset:37888
	ds_read_b128 v[228:231], v150 offset:38912
	global_load_lds_dwordx4 v130, s[24:25]
	s_mov_b32 m0, s16
	ds_read_b128 v[232:235], v150 offset:39936
	global_load_lds_dwordx4 v132, s[24:25]
	s_waitcnt vmcnt(8)
	s_waitcnt lgkmcnt(0)
	s_barrier
	s_setprio 1
	s_waitcnt lgkmcnt(0)
	v_mfma_f32_16x16x32_bf16 v[126:129], v[138:141], v[204:207], v[126:129]
	v_mfma_f32_16x16x32_bf16 v[122:125], v[154:157], v[204:207], v[122:125]
	v_mfma_f32_16x16x32_bf16 v[118:121], v[138:141], v[212:215], v[118:121]
	v_mfma_f32_16x16x32_bf16 v[114:117], v[154:157], v[212:215], v[114:117]
	v_mfma_f32_16x16x32_bf16 v[110:113], v[138:141], v[220:223], v[110:113]
	v_mfma_f32_16x16x32_bf16 v[106:109], v[154:157], v[220:223], v[106:109]
	v_mfma_f32_16x16x32_bf16 v[102:105], v[138:141], v[228:231], v[102:105]
	v_mfma_f32_16x16x32_bf16 v[98:101], v[154:157], v[228:231], v[98:101]
	v_mfma_f32_16x16x32_bf16 v[126:129], v[142:145], v[208:211], v[126:129]
	v_mfma_f32_16x16x32_bf16 v[122:125], v[158:161], v[208:211], v[122:125]
	v_mfma_f32_16x16x32_bf16 v[118:121], v[142:145], v[216:219], v[118:121]
	v_mfma_f32_16x16x32_bf16 v[114:117], v[158:161], v[216:219], v[114:117]
	v_mfma_f32_16x16x32_bf16 v[110:113], v[142:145], v[224:227], v[110:113]
	v_mfma_f32_16x16x32_bf16 v[106:109], v[158:161], v[224:227], v[106:109]
	v_mfma_f32_16x16x32_bf16 v[102:105], v[142:145], v[232:235], v[102:105]
	v_mfma_f32_16x16x32_bf16 v[98:101], v[158:161], v[232:235], v[98:101]
	s_setprio 0
	s_setprio 1
	v_mfma_f32_16x16x32_bf16 v[94:97], v[168:171], v[204:207], v[94:97]
	v_mfma_f32_16x16x32_bf16 v[90:93], v[196:199], v[204:207], v[90:93]
	v_mfma_f32_16x16x32_bf16 v[86:89], v[168:171], v[212:215], v[86:89]
	v_mfma_f32_16x16x32_bf16 v[82:85], v[196:199], v[212:215], v[82:85]
	v_mfma_f32_16x16x32_bf16 v[78:81], v[168:171], v[220:223], v[78:81]
	v_mfma_f32_16x16x32_bf16 v[74:77], v[196:199], v[220:223], v[74:77]
	v_mfma_f32_16x16x32_bf16 v[70:73], v[168:171], v[228:231], v[70:73]
	v_mfma_f32_16x16x32_bf16 v[66:69], v[196:199], v[228:231], v[66:69]
	v_mfma_f32_16x16x32_bf16 v[94:97], v[192:195], v[208:211], v[94:97]
	v_mfma_f32_16x16x32_bf16 v[90:93], v[200:203], v[208:211], v[90:93]
	v_mfma_f32_16x16x32_bf16 v[86:89], v[192:195], v[216:219], v[86:89]
	v_mfma_f32_16x16x32_bf16 v[82:85], v[200:203], v[216:219], v[82:85]
	v_mfma_f32_16x16x32_bf16 v[78:81], v[192:195], v[224:227], v[78:81]
	v_mfma_f32_16x16x32_bf16 v[74:77], v[200:203], v[224:227], v[74:77]
	v_mfma_f32_16x16x32_bf16 v[70:73], v[192:195], v[232:235], v[70:73]
	v_mfma_f32_16x16x32_bf16 v[66:69], v[200:203], v[232:235], v[66:69]
	s_setprio 0
	s_barrier
	s_mov_b32 m0, s19
	s_add_u32 s24, s86, 0x40080
	ds_read_b128 v[204:207], v150 offset:49152
	ds_read_b128 v[208:211], v150 offset:50176
	ds_read_b128 v[212:215], v150 offset:51200
	ds_read_b128 v[216:219], v150 offset:52224
	global_load_lds_dwordx4 v164, s[86:87]
	s_mov_b32 m0, s28
	s_addc_u32 s25, s87, 0
	global_load_lds_dwordx4 v165, s[86:87]
	s_mov_b32 m0, s69
	ds_read_b128 v[232:235], v150 offset:56320
	global_load_lds_dwordx4 v130, s[24:25]
	s_mov_b32 m0, s20
	ds_read_b128 v[228:231], v150 offset:55296
	global_load_lds_dwordx4 v132, s[24:25]
	s_mov_b32 m0, s57
	ds_read_b128 v[224:227], v150 offset:54272
	global_load_lds_dwordx4 v164, s[90:91]
	s_mov_b32 m0, s68
	ds_read_b128 v[220:223], v150 offset:53248
	global_load_lds_dwordx4 v165, s[90:91]
	s_waitcnt vmcnt(8)
	s_waitcnt lgkmcnt(0)
	s_barrier
	s_setprio 1
	s_waitcnt lgkmcnt(0)
	v_mfma_f32_16x16x32_bf16 v[62:65], v[138:141], v[204:207], v[62:65]
	v_mfma_f32_16x16x32_bf16 v[58:61], v[154:157], v[204:207], v[58:61]
	v_mfma_f32_16x16x32_bf16 v[54:57], v[138:141], v[212:215], v[54:57]
	v_mfma_f32_16x16x32_bf16 v[50:53], v[154:157], v[212:215], v[50:53]
	v_mfma_f32_16x16x32_bf16 v[46:49], v[138:141], v[220:223], v[46:49]
	v_mfma_f32_16x16x32_bf16 v[42:45], v[154:157], v[220:223], v[42:45]
	v_mfma_f32_16x16x32_bf16 v[38:41], v[138:141], v[228:231], v[38:41]
	v_mfma_f32_16x16x32_bf16 v[34:37], v[154:157], v[228:231], v[34:37]
	v_mfma_f32_16x16x32_bf16 v[62:65], v[142:145], v[208:211], v[62:65]
	v_mfma_f32_16x16x32_bf16 v[58:61], v[158:161], v[208:211], v[58:61]
	v_mfma_f32_16x16x32_bf16 v[54:57], v[142:145], v[216:219], v[54:57]
	v_mfma_f32_16x16x32_bf16 v[50:53], v[158:161], v[216:219], v[50:53]
	v_mfma_f32_16x16x32_bf16 v[46:49], v[142:145], v[224:227], v[46:49]
	v_mfma_f32_16x16x32_bf16 v[42:45], v[158:161], v[224:227], v[42:45]
	v_mfma_f32_16x16x32_bf16 v[38:41], v[142:145], v[232:235], v[38:41]
	v_mfma_f32_16x16x32_bf16 v[34:37], v[158:161], v[232:235], v[34:37]
	s_setprio 0
	s_setprio 1
	v_mfma_f32_16x16x32_bf16 v[30:33], v[168:171], v[204:207], v[30:33]
	v_mfma_f32_16x16x32_bf16 v[26:29], v[196:199], v[204:207], v[26:29]
	v_mfma_f32_16x16x32_bf16 v[22:25], v[168:171], v[212:215], v[22:25]
	v_mfma_f32_16x16x32_bf16 v[18:21], v[196:199], v[212:215], v[18:21]
	v_mfma_f32_16x16x32_bf16 v[14:17], v[168:171], v[220:223], v[14:17]
	v_mfma_f32_16x16x32_bf16 v[10:13], v[196:199], v[220:223], v[10:13]
	v_mfma_f32_16x16x32_bf16 v[6:9], v[168:171], v[228:231], v[6:9]
	v_mfma_f32_16x16x32_bf16 v[2:5], v[196:199], v[228:231], v[2:5]
	v_mfma_f32_16x16x32_bf16 v[30:33], v[192:195], v[208:211], v[30:33]
	v_mfma_f32_16x16x32_bf16 v[26:29], v[200:203], v[208:211], v[26:29]
	v_mfma_f32_16x16x32_bf16 v[22:25], v[192:195], v[216:219], v[22:25]
	v_mfma_f32_16x16x32_bf16 v[18:21], v[200:203], v[216:219], v[18:21]
	v_mfma_f32_16x16x32_bf16 v[14:17], v[192:195], v[224:227], v[14:17]
	v_mfma_f32_16x16x32_bf16 v[10:13], v[200:203], v[224:227], v[10:13]
	v_mfma_f32_16x16x32_bf16 v[6:9], v[192:195], v[232:235], v[6:9]
	v_mfma_f32_16x16x32_bf16 v[2:5], v[200:203], v[232:235], v[2:5]
	s_setprio 0
	s_barrier
	s_add_i32 vcc_lo, vcc_lo, 2
	s_add_u32 s50, s50, 0x100
	s_addc_u32 s51, s51, 0
	s_cmp_gt_u32 vcc_lo, 13
	s_mov_b64 s[34:35], s[40:41]
	s_cbranch_scc0 .LBB0_381
	s_and_b64 vcc, exec, s[42:43]
	s_cbranch_vccz .LBB0_384
	s_barrier

; #define PG8_STAGE(bufoff, gbase) do { _Pragma("unroll") for (int _i = 0; _i < 2; ++_i) \
;     __builtin_amdgcn_global_load_lds((const unsigned*)((const char*)(gbase) + voff[_i]), (LAS unsigned*)(lds + (bufoff) + ldsw + _i * 8192), 16, 0, 0); } while (0)
; #define PG8_LDA(dst, b, h) do { _Pragma("unroll") for (int m = 0; m < 4; ++m) _Pragma("unroll") for (int k = 0; k < 2; ++k) dst[m][k] = *(const LAS bf16x8*)(lds + PG8_SA(b, h) + aoff + m * 2048 + k * 1024); } while (0)
; #define PG8_LDB(dst, b, h) do { _Pragma("unroll") for (int n = 0; n < 2; ++n) _Pragma("unroll") for (int k = 0; k < 2; ++k) dst[n][k] = *(const LAS bf16x8*)(lds + PG8_SB(b, h) + boff + n * 2048 + k * 1024); } while (0)
; #define PG8_WAIT_V(n) asm volatile("s_waitcnt vmcnt(" #n ")" ::: "memory")
; #define PG8_WAIT_L(n) asm volatile("s_waitcnt lgkmcnt(" #n ")" ::: "memory")
; #define PG8_BAR __builtin_amdgcn_s_barrier()
; #define PG8_SCHED __builtin_amdgcn_sched_barrier(0)
; template <int EPI, bool ALIGN_EPI = true, bool SP2 = true>
; DI void gemm8_phase(const GemmArgs& g, char* lds_) {
;     ...
;         PG8_LDB(B0, 0, 0); PG8_LDB(B1, 0, 1); PG8_SCHED; PG8_LDA(At, 0, 0); PG8_STAGE(PG8_SA(1, 1), a1 + hstep);
;         if (relax) PG8_WAIT_V(24); else PG8_WAIT_V(8);
;         PG8_WAIT_L(0); PG8_BAR; PG8_MMA(0, 0, At, B0); PG8_MMA(0, 1, At, B1); PG8_BAR; PG8_SCHED;
;         PG8_LDA(At, 0, 1); PG8_STAGE(PG8_SB(0, 0), b2); PG8_STAGE(PG8_SB(0, 1), b2 + hstep); PG8_STAGE(PG8_SA(0, 0), a2);
;         if (relax) PG8_WAIT_V(24); else PG8_WAIT_V(8);
;         PG8_WAIT_L(0); PG8_BAR; PG8_MMA(1, 0, At, B0); PG8_MMA(1, 1, At, B1); PG8_BAR; PG8_SCHED;
;         PG8_LDB(B0, 1, 0); PG8_LDB(B1, 1, 1); PG8_SCHED; PG8_LDA(At, 1, 0); PG8_STAGE(PG8_SA(0, 1), a2 + hstep);
.LBB0_573:
	ds_read_b128 v[146:149], v172
	ds_read_b128 v[150:153], v172 offset:1024
	ds_read_b128 v[154:157], v172 offset:2048
	ds_read_b128 v[158:161], v172 offset:3072
	ds_read_b128 v[168:171], v172 offset:16384
	ds_read_b128 v[192:195], v172 offset:17408
	ds_read_b128 v[196:199], v172 offset:18432
	ds_read_b128 v[200:203], v172 offset:19456
	s_add_u32 s40, s38, 0x100
	s_addc_u32 s41, s39, 0
	s_cmp_eq_u32 s69, 12
	s_cselect_b32 s91, s49, s41
	s_cselect_b32 s90, s48, s40
	s_cselect_b32 s87, s45, s51
	s_cselect_b32 s86, s47, s50
	s_add_i32 m0, s9, 0xc000
	ds_read_b128 v[204:207], v141
	ds_read_b128 v[208:211], v141 offset:1024
	ds_read_b128 v[212:215], v141 offset:2048
	ds_read_b128 v[216:219], v141 offset:3072
	ds_read_b128 v[220:223], v141 offset:4096
	ds_read_b128 v[224:227], v141 offset:5120
	ds_read_b128 v[228:231], v141 offset:6144
	global_load_lds_dwordx4 v134, s[38:39]
	s_add_i32 m0, s9, 0xe000
	ds_read_b128 v[232:235], v141 offset:7168
	global_load_lds_dwordx4 v136, s[38:39]
	s_waitcnt vmcnt(8)
	s_waitcnt lgkmcnt(0)
	s_barrier
	s_setprio 1
	s_waitcnt lgkmcnt(0)
	v_mfma_f32_16x16x32_bf16 v[126:129], v[146:149], v[204:207], v[126:129]
	v_mfma_f32_16x16x32_bf16 v[114:117], v[154:157], v[204:207], v[114:117]
	v_mfma_f32_16x16x32_bf16 v[122:125], v[146:149], v[212:215], v[122:125]
	v_mfma_f32_16x16x32_bf16 v[106:109], v[154:157], v[212:215], v[106:109]
	v_mfma_f32_16x16x32_bf16 v[118:121], v[146:149], v[220:223], v[118:121]
	v_mfma_f32_16x16x32_bf16 v[102:105], v[154:157], v[220:223], v[102:105]
	v_mfma_f32_16x16x32_bf16 v[110:113], v[146:149], v[228:231], v[110:113]
	v_mfma_f32_16x16x32_bf16 v[98:101], v[154:157], v[228:231], v[98:101]
	v_mfma_f32_16x16x32_bf16 v[126:129], v[150:153], v[208:211], v[126:129]
	v_mfma_f32_16x16x32_bf16 v[114:117], v[158:161], v[208:211], v[114:117]
	v_mfma_f32_16x16x32_bf16 v[122:125], v[150:153], v[216:219], v[122:125]
	v_mfma_f32_16x16x32_bf16 v[106:109], v[158:161], v[216:219], v[106:109]
	v_mfma_f32_16x16x32_bf16 v[118:121], v[150:153], v[224:227], v[118:121]
	v_mfma_f32_16x16x32_bf16 v[102:105], v[158:161], v[224:227], v[102:105]
	v_mfma_f32_16x16x32_bf16 v[110:113], v[150:153], v[232:235], v[110:113]
	v_mfma_f32_16x16x32_bf16 v[98:101], v[158:161], v[232:235], v[98:101]
	s_setprio 0
	s_setprio 1
	v_mfma_f32_16x16x32_bf16 v[94:97], v[168:171], v[204:207], v[94:97]
	v_mfma_f32_16x16x32_bf16 v[90:93], v[196:199], v[204:207], v[90:93]
	v_mfma_f32_16x16x32_bf16 v[86:89], v[168:171], v[212:215], v[86:89]
	v_mfma_f32_16x16x32_bf16 v[82:85], v[196:199], v[212:215], v[82:85]
	v_mfma_f32_16x16x32_bf16 v[78:81], v[168:171], v[220:223], v[78:81]
	v_mfma_f32_16x16x32_bf16 v[74:77], v[196:199], v[220:223], v[74:77]
	v_mfma_f32_16x16x32_bf16 v[70:73], v[168:171], v[228:231], v[70:73]
	v_mfma_f32_16x16x32_bf16 v[66:69], v[196:199], v[228:231], v[66:69]
	v_mfma_f32_16x16x32_bf16 v[94:97], v[192:195], v[208:211], v[94:97]
	v_mfma_f32_16x16x32_bf16 v[90:93], v[200:203], v[208:211], v[90:93]
	v_mfma_f32_16x16x32_bf16 v[86:89], v[192:195], v[216:219], v[86:89]
	v_mfma_f32_16x16x32_bf16 v[82:85], v[200:203], v[216:219], v[82:85]
	v_mfma_f32_16x16x32_bf16 v[78:81], v[192:195], v[224:227], v[78:81]
	v_mfma_f32_16x16x32_bf16 v[74:77], v[200:203], v[224:227], v[74:77]
	v_mfma_f32_16x16x32_bf16 v[70:73], v[192:195], v[232:235], v[70:73]
	v_mfma_f32_16x16x32_bf16 v[66:69], v[200:203], v[232:235], v[66:69]
	s_setprio 0
	s_barrier
	s_mov_b32 m0, s10
	s_add_u32 s24, s86, 0x40000
	ds_read_b128 v[204:207], v141 offset:16384
	ds_read_b128 v[208:211], v141 offset:17408
	ds_read_b128 v[212:215], v141 offset:18432
	ds_read_b128 v[216:219], v141 offset:19456
	global_load_lds_dwordx4 v130, s[86:87]
	s_mov_b32 m0, s11
	s_addc_u32 s25, s87, 0
	global_load_lds_dwordx4 v132, s[86:87]
	s_mov_b32 m0, s12
	ds_read_b128 v[232:235], v141 offset:23552
	global_load_lds_dwordx4 v130, s[24:25]
	s_mov_b32 m0, s13
	ds_read_b128 v[228:231], v141 offset:22528
	global_load_lds_dwordx4 v132, s[24:25]
	s_mov_b32 m0, s9
	ds_read_b128 v[224:227], v141 offset:21504
	global_load_lds_dwordx4 v130, s[90:91]
	s_mov_b32 m0, s14
	ds_read_b128 v[220:223], v141 offset:20480
	global_load_lds_dwordx4 v132, s[90:91]
	s_waitcnt vmcnt(8)
	s_waitcnt lgkmcnt(0)
	s_barrier
	s_setprio 1
	s_waitcnt lgkmcnt(0)
	v_mfma_f32_16x16x32_bf16 v[62:65], v[146:149], v[204:207], v[62:65]
	v_mfma_f32_16x16x32_bf16 v[50:53], v[154:157], v[204:207], v[50:53]
	v_mfma_f32_16x16x32_bf16 v[58:61], v[146:149], v[212:215], v[58:61]
	v_mfma_f32_16x16x32_bf16 v[42:45], v[154:157], v[212:215], v[42:45]
	v_mfma_f32_16x16x32_bf16 v[54:57], v[146:149], v[220:223], v[54:57]
	v_mfma_f32_16x16x32_bf16 v[38:41], v[154:157], v[220:223], v[38:41]
	v_mfma_f32_16x16x32_bf16 v[46:49], v[146:149], v[228:231], v[46:49]
	v_mfma_f32_16x16x32_bf16 v[34:37], v[154:157], v[228:231], v[34:37]
	v_mfma_f32_16x16x32_bf16 v[62:65], v[150:153], v[208:211], v[62:65]
	v_mfma_f32_16x16x32_bf16 v[50:53], v[158:161], v[208:211], v[50:53]
	v_mfma_f32_16x16x32_bf16 v[58:61], v[150:153], v[216:219], v[58:61]
	v_mfma_f32_16x16x32_bf16 v[42:45], v[158:161], v[216:219], v[42:45]
	v_mfma_f32_16x16x32_bf16 v[54:57], v[150:153], v[224:227], v[54:57]
	v_mfma_f32_16x16x32_bf16 v[38:41], v[158:161], v[224:227], v[38:41]
	v_mfma_f32_16x16x32_bf16 v[46:49], v[150:153], v[232:235], v[46:49]
	v_mfma_f32_16x16x32_bf16 v[34:37], v[158:161], v[232:235], v[34:37]
	s_setprio 0
	s_setprio 1
	v_mfma_f32_16x16x32_bf16 v[30:33], v[168:171], v[204:207], v[30:33]
	v_mfma_f32_16x16x32_bf16 v[26:29], v[196:199], v[204:207], v[26:29]
	v_mfma_f32_16x16x32_bf16 v[22:25], v[168:171], v[212:215], v[22:25]
	v_mfma_f32_16x16x32_bf16 v[18:21], v[196:199], v[212:215], v[18:21]
	v_mfma_f32_16x16x32_bf16 v[14:17], v[168:171], v[220:223], v[14:17]
	v_mfma_f32_16x16x32_bf16 v[10:13], v[196:199], v[220:223], v[10:13]
	v_mfma_f32_16x16x32_bf16 v[6:9], v[168:171], v[228:231], v[6:9]
	v_mfma_f32_16x16x32_bf16 v[2:5], v[196:199], v[228:231], v[2:5]
	v_mfma_f32_16x16x32_bf16 v[30:33], v[192:195], v[208:211], v[30:33]
	v_mfma_f32_16x16x32_bf16 v[26:29], v[200:203], v[208:211], v[26:29]
	v_mfma_f32_16x16x32_bf16 v[22:25], v[192:195], v[216:219], v[22:25]
	v_mfma_f32_16x16x32_bf16 v[18:21], v[200:203], v[216:219], v[18:21]
	v_mfma_f32_16x16x32_bf16 v[14:17], v[192:195], v[224:227], v[14:17]
	v_mfma_f32_16x16x32_bf16 v[10:13], v[200:203], v[224:227], v[10:13]
	v_mfma_f32_16x16x32_bf16 v[6:9], v[192:195], v[232:235], v[6:9]
	v_mfma_f32_16x16x32_bf16 v[2:5], v[200:203], v[232:235], v[2:5]
	s_setprio 0
	s_barrier
; #define PG8_STAGE(bufoff, gbase) do { _Pragma("unroll") for (int _i = 0; _i < 2; ++_i) \
;     __builtin_amdgcn_global_load_lds((const unsigned*)((const char*)(gbase) + voff[_i]), (LAS unsigned*)(lds + (bufoff) + ldsw + _i * 8192), 16, 0, 0); } while (0)
; #define PG8_LDA(dst, b, h) do { _Pragma("unroll") for (int m = 0; m < 4; ++m) _Pragma("unroll") for (int k = 0; k < 2; ++k) dst[m][k] = *(const LAS bf16x8*)(lds + PG8_SA(b, h) + aoff + m * 2048 + k * 1024); } while (0)
; #define PG8_LDB(dst, b, h) do { _Pragma("unroll") for (int n = 0; n < 2; ++n) _Pragma("unroll") for (int k = 0; k < 2; ++k) dst[n][k] = *(const LAS bf16x8*)(lds + PG8_SB(b, h) + boff + n * 2048 + k * 1024); } while (0)
; #define PG8_WAIT_V(n) asm volatile("s_waitcnt vmcnt(" #n ")" ::: "memory")
; #define PG8_WAIT_L(n) asm volatile("s_waitcnt lgkmcnt(" #n ")" ::: "memory")
; #define PG8_BAR __builtin_amdgcn_s_barrier()
; #define PG8_SCHED __builtin_amdgcn_sched_barrier(0)
; template <int EPI, bool ALIGN_EPI = true, bool SP2 = true>
; DI void gemm8_phase(const GemmArgs& g, char* lds_) {
;     ...
;         PG8_LDB(B0, 1, 0); PG8_LDB(B1, 1, 1); PG8_SCHED; PG8_LDA(At, 1, 0); PG8_STAGE(PG8_SA(0, 1), a2 + hstep);
;         PG8_WAIT_V(8); PG8_WAIT_L(0); PG8_BAR; PG8_MMA(0, 0, At, B0); PG8_MMA(0, 1, At, B1); PG8_BAR; PG8_SCHED;
;         PG8_LDA(At, 1, 1); PG8_STAGE(PG8_SB(1, 0), b3); PG8_STAGE(PG8_SB(1, 1), b3 + hstep); PG8_STAGE(PG8_SA(1, 0), a3);
;         PG8_WAIT_V(8); PG8_WAIT_L(0); PG8_BAR; PG8_MMA(1, 0, At, B0); PG8_MMA(1, 1, At, B1); PG8_BAR; PG8_SCHED;
	ds_read_b128 v[146:149], v172 offset:32768
	ds_read_b128 v[150:153], v172 offset:33792
	ds_read_b128 v[154:157], v172 offset:34816
	ds_read_b128 v[158:161], v172 offset:35840
	ds_read_b128 v[168:171], v172 offset:49152
	ds_read_b128 v[192:195], v172 offset:50176
	ds_read_b128 v[196:199], v172 offset:51200
	ds_read_b128 v[200:203], v172 offset:52224
	s_add_u32 s24, s90, 0x40000
	s_addc_u32 s25, s91, 0
	s_mov_b32 m0, s15
	ds_read_b128 v[204:207], v141 offset:32768
	ds_read_b128 v[208:211], v141 offset:33792
	ds_read_b128 v[212:215], v141 offset:34816
	ds_read_b128 v[216:219], v141 offset:35840
	ds_read_b128 v[220:223], v141 offset:36864
	ds_read_b128 v[224:227], v141 offset:37888
	ds_read_b128 v[228:231], v141 offset:38912
	global_load_lds_dwordx4 v130, s[24:25]
	s_mov_b32 m0, s16
	ds_read_b128 v[232:235], v141 offset:39936
	global_load_lds_dwordx4 v132, s[24:25]
	s_waitcnt vmcnt(8)
	s_waitcnt lgkmcnt(0)
	s_barrier
	s_setprio 1
	s_waitcnt lgkmcnt(0)
	v_mfma_f32_16x16x32_bf16 v[126:129], v[146:149], v[204:207], v[126:129]
	v_mfma_f32_16x16x32_bf16 v[114:117], v[154:157], v[204:207], v[114:117]
	v_mfma_f32_16x16x32_bf16 v[122:125], v[146:149], v[212:215], v[122:125]
	v_mfma_f32_16x16x32_bf16 v[106:109], v[154:157], v[212:215], v[106:109]
	v_mfma_f32_16x16x32_bf16 v[118:121], v[146:149], v[220:223], v[118:121]
	v_mfma_f32_16x16x32_bf16 v[102:105], v[154:157], v[220:223], v[102:105]
	v_mfma_f32_16x16x32_bf16 v[110:113], v[146:149], v[228:231], v[110:113]
	v_mfma_f32_16x16x32_bf16 v[98:101], v[154:157], v[228:231], v[98:101]
	v_mfma_f32_16x16x32_bf16 v[126:129], v[150:153], v[208:211], v[126:129]
	v_mfma_f32_16x16x32_bf16 v[114:117], v[158:161], v[208:211], v[114:117]
	v_mfma_f32_16x16x32_bf16 v[122:125], v[150:153], v[216:219], v[122:125]
	v_mfma_f32_16x16x32_bf16 v[106:109], v[158:161], v[216:219], v[106:109]
	v_mfma_f32_16x16x32_bf16 v[118:121], v[150:153], v[224:227], v[118:121]
	v_mfma_f32_16x16x32_bf16 v[102:105], v[158:161], v[224:227], v[102:105]
	v_mfma_f32_16x16x32_bf16 v[110:113], v[150:153], v[232:235], v[110:113]
	v_mfma_f32_16x16x32_bf16 v[98:101], v[158:161], v[232:235], v[98:101]
	s_setprio 0
	s_setprio 1
	v_mfma_f32_16x16x32_bf16 v[94:97], v[168:171], v[204:207], v[94:97]
	v_mfma_f32_16x16x32_bf16 v[90:93], v[196:199], v[204:207], v[90:93]
	v_mfma_f32_16x16x32_bf16 v[86:89], v[168:171], v[212:215], v[86:89]
	v_mfma_f32_16x16x32_bf16 v[82:85], v[196:199], v[212:215], v[82:85]
	v_mfma_f32_16x16x32_bf16 v[78:81], v[168:171], v[220:223], v[78:81]
	v_mfma_f32_16x16x32_bf16 v[74:77], v[196:199], v[220:223], v[74:77]
	v_mfma_f32_16x16x32_bf16 v[70:73], v[168:171], v[228:231], v[70:73]
	v_mfma_f32_16x16x32_bf16 v[66:69], v[196:199], v[228:231], v[66:69]
	v_mfma_f32_16x16x32_bf16 v[94:97], v[192:195], v[208:211], v[94:97]
	v_mfma_f32_16x16x32_bf16 v[90:93], v[200:203], v[208:211], v[90:93]
	v_mfma_f32_16x16x32_bf16 v[86:89], v[192:195], v[216:219], v[86:89]
	v_mfma_f32_16x16x32_bf16 v[82:85], v[200:203], v[216:219], v[82:85]
	v_mfma_f32_16x16x32_bf16 v[78:81], v[192:195], v[224:227], v[78:81]
	v_mfma_f32_16x16x32_bf16 v[74:77], v[200:203], v[224:227], v[74:77]
	v_mfma_f32_16x16x32_bf16 v[70:73], v[192:195], v[232:235], v[70:73]
	v_mfma_f32_16x16x32_bf16 v[66:69], v[200:203], v[232:235], v[66:69]
	s_setprio 0
	s_barrier
	s_mov_b32 m0, s18
	s_add_u32 s24, s86, 0x40080
	ds_read_b128 v[204:207], v141 offset:49152
	ds_read_b128 v[208:211], v141 offset:50176
	ds_read_b128 v[212:215], v141 offset:51200
	ds_read_b128 v[216:219], v141 offset:52224
	global_load_lds_dwordx4 v164, s[86:87]
	s_mov_b32 m0, s19
	s_addc_u32 s25, s87, 0
	global_load_lds_dwordx4 v165, s[86:87]
	s_mov_b32 m0, s28
	ds_read_b128 v[232:235], v141 offset:56320
	global_load_lds_dwordx4 v130, s[24:25]
	s_mov_b32 m0, s57
	ds_read_b128 v[228:231], v141 offset:55296
	global_load_lds_dwordx4 v132, s[24:25]
	s_mov_b32 m0, s20
	ds_read_b128 v[224:227], v141 offset:54272
	global_load_lds_dwordx4 v164, s[90:91]
	s_mov_b32 m0, s21
	ds_read_b128 v[220:223], v141 offset:53248
	global_load_lds_dwordx4 v165, s[90:91]
	s_waitcnt vmcnt(8)
	s_waitcnt lgkmcnt(0)
	s_barrier
	s_setprio 1
	s_waitcnt lgkmcnt(0)
	v_mfma_f32_16x16x32_bf16 v[62:65], v[146:149], v[204:207], v[62:65]
	v_mfma_f32_16x16x32_bf16 v[50:53], v[154:157], v[204:207], v[50:53]
	v_mfma_f32_16x16x32_bf16 v[58:61], v[146:149], v[212:215], v[58:61]
	v_mfma_f32_16x16x32_bf16 v[42:45], v[154:157], v[212:215], v[42:45]
	v_mfma_f32_16x16x32_bf16 v[54:57], v[146:149], v[220:223], v[54:57]
	v_mfma_f32_16x16x32_bf16 v[38:41], v[154:157], v[220:223], v[38:41]
	v_mfma_f32_16x16x32_bf16 v[46:49], v[146:149], v[228:231], v[46:49]
	v_mfma_f32_16x16x32_bf16 v[34:37], v[154:157], v[228:231], v[34:37]
	v_mfma_f32_16x16x32_bf16 v[62:65], v[150:153], v[208:211], v[62:65]
	v_mfma_f32_16x16x32_bf16 v[50:53], v[158:161], v[208:211], v[50:53]
	v_mfma_f32_16x16x32_bf16 v[58:61], v[150:153], v[216:219], v[58:61]
	v_mfma_f32_16x16x32_bf16 v[42:45], v[158:161], v[216:219], v[42:45]
	v_mfma_f32_16x16x32_bf16 v[54:57], v[150:153], v[224:227], v[54:57]
	v_mfma_f32_16x16x32_bf16 v[38:41], v[158:161], v[224:227], v[38:41]
	v_mfma_f32_16x16x32_bf16 v[46:49], v[150:153], v[232:235], v[46:49]
	v_mfma_f32_16x16x32_bf16 v[34:37], v[158:161], v[232:235], v[34:37]
	s_setprio 0
	s_setprio 1
	v_mfma_f32_16x16x32_bf16 v[30:33], v[168:171], v[204:207], v[30:33]
	v_mfma_f32_16x16x32_bf16 v[26:29], v[196:199], v[204:207], v[26:29]
	v_mfma_f32_16x16x32_bf16 v[22:25], v[168:171], v[212:215], v[22:25]
	v_mfma_f32_16x16x32_bf16 v[18:21], v[196:199], v[212:215], v[18:21]
	v_mfma_f32_16x16x32_bf16 v[14:17], v[168:171], v[220:223], v[14:17]
	v_mfma_f32_16x16x32_bf16 v[10:13], v[196:199], v[220:223], v[10:13]
	v_mfma_f32_16x16x32_bf16 v[6:9], v[168:171], v[228:231], v[6:9]
	v_mfma_f32_16x16x32_bf16 v[2:5], v[196:199], v[228:231], v[2:5]
	v_mfma_f32_16x16x32_bf16 v[30:33], v[192:195], v[208:211], v[30:33]
	v_mfma_f32_16x16x32_bf16 v[26:29], v[200:203], v[208:211], v[26:29]
	v_mfma_f32_16x16x32_bf16 v[22:25], v[192:195], v[216:219], v[22:25]
	v_mfma_f32_16x16x32_bf16 v[18:21], v[200:203], v[216:219], v[18:21]
	v_mfma_f32_16x16x32_bf16 v[14:17], v[192:195], v[224:227], v[14:17]
	v_mfma_f32_16x16x32_bf16 v[10:13], v[200:203], v[224:227], v[10:13]
	v_mfma_f32_16x16x32_bf16 v[6:9], v[192:195], v[232:235], v[6:9]
	v_mfma_f32_16x16x32_bf16 v[2:5], v[200:203], v[232:235], v[2:5]
	s_setprio 0
	s_barrier
	s_add_i32 s69, s69, 2
	s_add_u32 s50, s50, 0x100
	s_addc_u32 s51, s51, 0
	s_cmp_gt_u32 s69, 13
	s_mov_b64 s[38:39], s[40:41]
	s_cbranch_scc0 .LBB0_573
	s_and_b64 vcc, exec, s[42:43]
	s_cbranch_vccz .LBB0_576
	s_barrier

; #define PG8_STAGE(bufoff, gbase) do { _Pragma("unroll") for (int _i = 0; _i < 2; ++_i) \
;     __builtin_amdgcn_global_load_lds((const unsigned*)((const char*)(gbase) + voff[_i]), (LAS unsigned*)(lds + (bufoff) + ldsw + _i * 8192), 16, 0, 0); } while (0)
; #define PG8_LDA(dst, b, h) do { _Pragma("unroll") for (int m = 0; m < 4; ++m) _Pragma("unroll") for (int k = 0; k < 2; ++k) dst[m][k] = *(const LAS bf16x8*)(lds + PG8_SA(b, h) + aoff + m * 2048 + k * 1024); } while (0)
; #define PG8_LDB(dst, b, h) do { _Pragma("unroll") for (int n = 0; n < 2; ++n) _Pragma("unroll") for (int k = 0; k < 2; ++k) dst[n][k] = *(const LAS bf16x8*)(lds + PG8_SB(b, h) + boff + n * 2048 + k * 1024); } while (0)
; #define PG8_WAIT_V(n) asm volatile("s_waitcnt vmcnt(" #n ")" ::: "memory")
; #define PG8_WAIT_L(n) asm volatile("s_waitcnt lgkmcnt(" #n ")" ::: "memory")
; #define PG8_BAR __builtin_amdgcn_s_barrier()
; #define PG8_SCHED __builtin_amdgcn_sched_barrier(0)
; template <int EPI, bool ALIGN_EPI = true, bool SP2 = true>
; DI void gemm8_phase(const GemmArgs& g, char* lds_) {
;     ...
; #pragma unroll 1
;     for (int t = 0; t < nt; t += 2) {
;       const bool last = (t == nt - 2);
;       const char* a1 = cA + (size_t)(t + 1) * kstep;
;       const char* a2 = last ? nA : cA + (size_t)(t + 2) * kstep;
;       const char* b2 = last ? nB : cB + (size_t)(t + 2) * kstep;
;       const char* a3 = a2 + kstep; const char* b3 = b2 + kstep;
;       if constexpr (SP2) {
;         const bool relax = EPI_VM > 0 && t == 0 && ui > 0;
;         PG8_LDB(B0, 0, 0); PG8_LDB(B1, 0, 1); PG8_SCHED; PG8_LDA(At, 0, 0); PG8_STAGE(PG8_SA(1, 1), a1 + hstep);
;         if (relax) PG8_WAIT_V(24); else PG8_WAIT_V(8);
;         PG8_WAIT_L(0); PG8_BAR; PG8_MMA(0, 0, At, B0); PG8_MMA(0, 1, At, B1); PG8_BAR; PG8_SCHED;
;         PG8_LDA(At, 0, 1); PG8_STAGE(PG8_SB(0, 0), b2); PG8_STAGE(PG8_SB(0, 1), b2 + hstep); PG8_STAGE(PG8_SA(0, 0), a2);
;         if (relax) PG8_WAIT_V(24); else PG8_WAIT_V(8);
;         PG8_WAIT_L(0); PG8_BAR; PG8_MMA(1, 0, At, B0); PG8_MMA(1, 1, At, B1); PG8_BAR; PG8_SCHED;
;         PG8_LDB(B0, 1, 0); PG8_LDB(B1, 1, 1); PG8_SCHED; PG8_LDA(At, 1, 0); PG8_STAGE(PG8_SA(0, 1), a2 + hstep);
.LBB0_1055:
	s_add_i32 s24, s62, 2
	ds_read_b128 v[130:133], v172
	ds_read_b128 v[134:137], v172 offset:1024
	ds_read_b128 v[138:141], v172 offset:2048
	ds_read_b128 v[142:145], v172 offset:3072
	ds_read_b128 v[146:149], v172 offset:16384
	ds_read_b128 v[150:153], v172 offset:17408
	ds_read_b128 v[154:157], v172 offset:18432
	ds_read_b128 v[158:161], v172 offset:19456
	s_add_u32 s25, s48, 0x80
	s_addc_u32 s26, s49, 0
	s_cmp_eq_u32 s87, s62
	s_cselect_b32 s62, s44, s25
	s_cselect_b32 s63, s45, s26
	s_cselect_b32 s27, s47, vcc_hi
	s_cselect_b32 s26, s46, vcc_lo
	s_add_i32 m0, s13, 0xc000
	ds_read_b128 v[194:197], v192
	ds_read_b128 v[198:201], v192 offset:1024
	ds_read_b128 v[202:205], v192 offset:2048
	ds_read_b128 v[206:209], v192 offset:3072
	ds_read_b128 v[210:213], v192 offset:4096
	ds_read_b128 v[214:217], v192 offset:5120
	ds_read_b128 v[218:221], v192 offset:6144
	global_load_lds_dwordx4 v168, s[48:49]
	s_add_i32 m0, s13, 0xe000
	ds_read_b128 v[222:225], v192 offset:7168
	global_load_lds_dwordx4 v170, s[48:49]
	s_waitcnt vmcnt(8)
	s_waitcnt lgkmcnt(0)
	s_barrier
	s_setprio 1
	s_waitcnt lgkmcnt(0)
	v_mfma_f32_16x16x32_bf16 v[126:129], v[130:133], v[194:197], v[126:129]
	v_mfma_f32_16x16x32_bf16 v[122:125], v[138:141], v[194:197], v[122:125]
	v_mfma_f32_16x16x32_bf16 v[118:121], v[130:133], v[202:205], v[118:121]
	v_mfma_f32_16x16x32_bf16 v[114:117], v[138:141], v[202:205], v[114:117]
	v_mfma_f32_16x16x32_bf16 v[110:113], v[130:133], v[210:213], v[110:113]
	v_mfma_f32_16x16x32_bf16 v[106:109], v[138:141], v[210:213], v[106:109]
	v_mfma_f32_16x16x32_bf16 v[102:105], v[130:133], v[218:221], v[102:105]
	v_mfma_f32_16x16x32_bf16 v[98:101], v[138:141], v[218:221], v[98:101]
	v_mfma_f32_16x16x32_bf16 v[126:129], v[134:137], v[198:201], v[126:129]
	v_mfma_f32_16x16x32_bf16 v[122:125], v[142:145], v[198:201], v[122:125]
	v_mfma_f32_16x16x32_bf16 v[118:121], v[134:137], v[206:209], v[118:121]
	v_mfma_f32_16x16x32_bf16 v[114:117], v[142:145], v[206:209], v[114:117]
	v_mfma_f32_16x16x32_bf16 v[110:113], v[134:137], v[214:217], v[110:113]
	v_mfma_f32_16x16x32_bf16 v[106:109], v[142:145], v[214:217], v[106:109]
	v_mfma_f32_16x16x32_bf16 v[102:105], v[134:137], v[222:225], v[102:105]
	v_mfma_f32_16x16x32_bf16 v[98:101], v[142:145], v[222:225], v[98:101]
	s_setprio 0
	s_setprio 1
	v_mfma_f32_16x16x32_bf16 v[94:97], v[146:149], v[194:197], v[94:97]
	v_mfma_f32_16x16x32_bf16 v[90:93], v[154:157], v[194:197], v[90:93]
	v_mfma_f32_16x16x32_bf16 v[86:89], v[146:149], v[202:205], v[86:89]
	v_mfma_f32_16x16x32_bf16 v[82:85], v[154:157], v[202:205], v[82:85]
	v_mfma_f32_16x16x32_bf16 v[78:81], v[146:149], v[210:213], v[78:81]
	v_mfma_f32_16x16x32_bf16 v[74:77], v[154:157], v[210:213], v[74:77]
	v_mfma_f32_16x16x32_bf16 v[70:73], v[146:149], v[218:221], v[70:73]
	v_mfma_f32_16x16x32_bf16 v[66:69], v[154:157], v[218:221], v[66:69]
	v_mfma_f32_16x16x32_bf16 v[94:97], v[150:153], v[198:201], v[94:97]
	v_mfma_f32_16x16x32_bf16 v[90:93], v[158:161], v[198:201], v[90:93]
	v_mfma_f32_16x16x32_bf16 v[86:89], v[150:153], v[206:209], v[86:89]
	v_mfma_f32_16x16x32_bf16 v[82:85], v[158:161], v[206:209], v[82:85]
	v_mfma_f32_16x16x32_bf16 v[78:81], v[150:153], v[214:217], v[78:81]
	v_mfma_f32_16x16x32_bf16 v[74:77], v[158:161], v[214:217], v[74:77]
	v_mfma_f32_16x16x32_bf16 v[70:73], v[150:153], v[222:225], v[70:73]
	v_mfma_f32_16x16x32_bf16 v[66:69], v[158:161], v[222:225], v[66:69]
	s_setprio 0
	s_barrier
	s_mov_b32 m0, s14
	ds_read_b128 v[194:197], v192 offset:16384
	ds_read_b128 v[198:201], v192 offset:17408
	ds_read_b128 v[202:205], v192 offset:18432
	global_load_lds_dwordx4 v0, s[26:27]
	s_mov_b32 m0, s15
	ds_read_b128 v[222:225], v192 offset:23552
	global_load_lds_dwordx4 v164, s[26:27]
	s_mov_b32 m0, s16
	ds_read_b128 v[218:221], v192 offset:22528
	global_load_lds_dwordx4 v228, s[26:27]
	s_mov_b32 m0, s17
	ds_read_b128 v[214:217], v192 offset:21504
	global_load_lds_dwordx4 v229, s[26:27]
	s_mov_b32 m0, s13
	ds_read_b128 v[210:213], v192 offset:20480
	global_load_lds_dwordx4 v0, s[62:63]
	s_mov_b32 m0, s18
	ds_read_b128 v[206:209], v192 offset:19456
	global_load_lds_dwordx4 v164, s[62:63]
	s_waitcnt vmcnt(8)
	s_waitcnt lgkmcnt(0)
	s_barrier
	s_setprio 1
	s_waitcnt lgkmcnt(0)
	v_mfma_f32_16x16x32_bf16 v[62:65], v[130:133], v[194:197], v[62:65]
	v_mfma_f32_16x16x32_bf16 v[58:61], v[138:141], v[194:197], v[58:61]
	v_mfma_f32_16x16x32_bf16 v[54:57], v[130:133], v[202:205], v[54:57]
	v_mfma_f32_16x16x32_bf16 v[50:53], v[138:141], v[202:205], v[50:53]
	v_mfma_f32_16x16x32_bf16 v[46:49], v[130:133], v[210:213], v[46:49]
	v_mfma_f32_16x16x32_bf16 v[42:45], v[138:141], v[210:213], v[42:45]
	v_mfma_f32_16x16x32_bf16 v[38:41], v[130:133], v[218:221], v[38:41]
	v_mfma_f32_16x16x32_bf16 v[34:37], v[138:141], v[218:221], v[34:37]
	v_mfma_f32_16x16x32_bf16 v[62:65], v[134:137], v[198:201], v[62:65]
	v_mfma_f32_16x16x32_bf16 v[58:61], v[142:145], v[198:201], v[58:61]
	v_mfma_f32_16x16x32_bf16 v[54:57], v[134:137], v[206:209], v[54:57]
	v_mfma_f32_16x16x32_bf16 v[50:53], v[142:145], v[206:209], v[50:53]
	v_mfma_f32_16x16x32_bf16 v[46:49], v[134:137], v[214:217], v[46:49]
	v_mfma_f32_16x16x32_bf16 v[42:45], v[142:145], v[214:217], v[42:45]
	v_mfma_f32_16x16x32_bf16 v[38:41], v[134:137], v[222:225], v[38:41]
	v_mfma_f32_16x16x32_bf16 v[34:37], v[142:145], v[222:225], v[34:37]
	s_setprio 0
	s_setprio 1
	v_mfma_f32_16x16x32_bf16 v[30:33], v[146:149], v[194:197], v[30:33]
	v_mfma_f32_16x16x32_bf16 v[26:29], v[154:157], v[194:197], v[26:29]
	v_mfma_f32_16x16x32_bf16 v[22:25], v[146:149], v[202:205], v[22:25]
	v_mfma_f32_16x16x32_bf16 v[18:21], v[154:157], v[202:205], v[18:21]
	v_mfma_f32_16x16x32_bf16 v[14:17], v[146:149], v[210:213], v[14:17]
	v_mfma_f32_16x16x32_bf16 v[10:13], v[154:157], v[210:213], v[10:13]
	v_mfma_f32_16x16x32_bf16 v[6:9], v[146:149], v[218:221], v[6:9]
	v_mfma_f32_16x16x32_bf16 v[2:5], v[154:157], v[218:221], v[2:5]
	v_mfma_f32_16x16x32_bf16 v[30:33], v[150:153], v[198:201], v[30:33]
	v_mfma_f32_16x16x32_bf16 v[26:29], v[158:161], v[198:201], v[26:29]
	v_mfma_f32_16x16x32_bf16 v[22:25], v[150:153], v[206:209], v[22:25]
	v_mfma_f32_16x16x32_bf16 v[18:21], v[158:161], v[206:209], v[18:21]
	v_mfma_f32_16x16x32_bf16 v[14:17], v[150:153], v[214:217], v[14:17]
	v_mfma_f32_16x16x32_bf16 v[10:13], v[158:161], v[214:217], v[10:13]
	v_mfma_f32_16x16x32_bf16 v[6:9], v[150:153], v[222:225], v[6:9]
	v_mfma_f32_16x16x32_bf16 v[2:5], v[158:161], v[222:225], v[2:5]
	s_setprio 0
	s_barrier
; #define PG8_STAGE(bufoff, gbase) do { _Pragma("unroll") for (int _i = 0; _i < 2; ++_i) \
;     __builtin_amdgcn_global_load_lds((const unsigned*)((const char*)(gbase) + voff[_i]), (LAS unsigned*)(lds + (bufoff) + ldsw + _i * 8192), 16, 0, 0); } while (0)
; #define PG8_LDA(dst, b, h) do { _Pragma("unroll") for (int m = 0; m < 4; ++m) _Pragma("unroll") for (int k = 0; k < 2; ++k) dst[m][k] = *(const LAS bf16x8*)(lds + PG8_SA(b, h) + aoff + m * 2048 + k * 1024); } while (0)
; #define PG8_LDB(dst, b, h) do { _Pragma("unroll") for (int n = 0; n < 2; ++n) _Pragma("unroll") for (int k = 0; k < 2; ++k) dst[n][k] = *(const LAS bf16x8*)(lds + PG8_SB(b, h) + boff + n * 2048 + k * 1024); } while (0)
; #define PG8_WAIT_V(n) asm volatile("s_waitcnt vmcnt(" #n ")" ::: "memory")
; #define PG8_WAIT_L(n) asm volatile("s_waitcnt lgkmcnt(" #n ")" ::: "memory")
; #define PG8_BAR __builtin_amdgcn_s_barrier()
; #define PG8_SCHED __builtin_amdgcn_sched_barrier(0)
; template <int EPI, bool ALIGN_EPI = true, bool SP2 = true>
; DI void gemm8_phase(const GemmArgs& g, char* lds_) {
;     ...
;         PG8_LDB(B0, 1, 0); PG8_LDB(B1, 1, 1); PG8_SCHED; PG8_LDA(At, 1, 0); PG8_STAGE(PG8_SA(0, 1), a2 + hstep);
;         PG8_WAIT_V(8); PG8_WAIT_L(0); PG8_BAR; PG8_MMA(0, 0, At, B0); PG8_MMA(0, 1, At, B1); PG8_BAR; PG8_SCHED;
;         PG8_LDA(At, 1, 1); PG8_STAGE(PG8_SB(1, 0), b3); PG8_STAGE(PG8_SB(1, 1), b3 + hstep); PG8_STAGE(PG8_SA(1, 0), a3);
;         PG8_WAIT_V(8); PG8_WAIT_L(0); PG8_BAR; PG8_MMA(1, 0, At, B0); PG8_MMA(1, 1, At, B1); PG8_BAR; PG8_SCHED;
	ds_read_b128 v[130:133], v172 offset:32768
	ds_read_b128 v[134:137], v172 offset:33792
	ds_read_b128 v[138:141], v172 offset:34816
	ds_read_b128 v[142:145], v172 offset:35840
	ds_read_b128 v[146:149], v172 offset:49152
	ds_read_b128 v[150:153], v172 offset:50176
	ds_read_b128 v[154:157], v172 offset:51200
	ds_read_b128 v[158:161], v172 offset:52224
	s_mov_b32 m0, s19
	ds_read_b128 v[194:197], v192 offset:32768
	ds_read_b128 v[198:201], v192 offset:33792
	ds_read_b128 v[202:205], v192 offset:34816
	ds_read_b128 v[206:209], v192 offset:35840
	ds_read_b128 v[210:213], v192 offset:36864
	ds_read_b128 v[214:217], v192 offset:37888
	ds_read_b128 v[218:221], v192 offset:38912
	global_load_lds_dwordx4 v228, s[62:63]
	s_mov_b32 m0, s20
	ds_read_b128 v[222:225], v192 offset:39936
	global_load_lds_dwordx4 v229, s[62:63]
	s_waitcnt vmcnt(8)
	s_waitcnt lgkmcnt(0)
	s_barrier
	s_setprio 1
	s_waitcnt lgkmcnt(0)
	v_mfma_f32_16x16x32_bf16 v[126:129], v[130:133], v[194:197], v[126:129]
	v_mfma_f32_16x16x32_bf16 v[122:125], v[138:141], v[194:197], v[122:125]
	v_mfma_f32_16x16x32_bf16 v[118:121], v[130:133], v[202:205], v[118:121]
	v_mfma_f32_16x16x32_bf16 v[114:117], v[138:141], v[202:205], v[114:117]
	v_mfma_f32_16x16x32_bf16 v[110:113], v[130:133], v[210:213], v[110:113]
	v_mfma_f32_16x16x32_bf16 v[106:109], v[138:141], v[210:213], v[106:109]
	v_mfma_f32_16x16x32_bf16 v[102:105], v[130:133], v[218:221], v[102:105]
	v_mfma_f32_16x16x32_bf16 v[98:101], v[138:141], v[218:221], v[98:101]
	v_mfma_f32_16x16x32_bf16 v[126:129], v[134:137], v[198:201], v[126:129]
	v_mfma_f32_16x16x32_bf16 v[122:125], v[142:145], v[198:201], v[122:125]
	v_mfma_f32_16x16x32_bf16 v[118:121], v[134:137], v[206:209], v[118:121]
	v_mfma_f32_16x16x32_bf16 v[114:117], v[142:145], v[206:209], v[114:117]
	v_mfma_f32_16x16x32_bf16 v[110:113], v[134:137], v[214:217], v[110:113]
	v_mfma_f32_16x16x32_bf16 v[106:109], v[142:145], v[214:217], v[106:109]
	v_mfma_f32_16x16x32_bf16 v[102:105], v[134:137], v[222:225], v[102:105]
	v_mfma_f32_16x16x32_bf16 v[98:101], v[142:145], v[222:225], v[98:101]
	s_setprio 0
	s_setprio 1
	v_mfma_f32_16x16x32_bf16 v[94:97], v[146:149], v[194:197], v[94:97]
	v_mfma_f32_16x16x32_bf16 v[90:93], v[154:157], v[194:197], v[90:93]
	v_mfma_f32_16x16x32_bf16 v[86:89], v[146:149], v[202:205], v[86:89]
	v_mfma_f32_16x16x32_bf16 v[82:85], v[154:157], v[202:205], v[82:85]
	v_mfma_f32_16x16x32_bf16 v[78:81], v[146:149], v[210:213], v[78:81]
	v_mfma_f32_16x16x32_bf16 v[74:77], v[154:157], v[210:213], v[74:77]
	v_mfma_f32_16x16x32_bf16 v[70:73], v[146:149], v[218:221], v[70:73]
	v_mfma_f32_16x16x32_bf16 v[66:69], v[154:157], v[218:221], v[66:69]
	v_mfma_f32_16x16x32_bf16 v[94:97], v[150:153], v[198:201], v[94:97]
	v_mfma_f32_16x16x32_bf16 v[90:93], v[158:161], v[198:201], v[90:93]
	v_mfma_f32_16x16x32_bf16 v[86:89], v[150:153], v[206:209], v[86:89]
	v_mfma_f32_16x16x32_bf16 v[82:85], v[158:161], v[206:209], v[82:85]
	v_mfma_f32_16x16x32_bf16 v[78:81], v[150:153], v[214:217], v[78:81]
	v_mfma_f32_16x16x32_bf16 v[74:77], v[158:161], v[214:217], v[74:77]
	v_mfma_f32_16x16x32_bf16 v[70:73], v[150:153], v[222:225], v[70:73]
	v_mfma_f32_16x16x32_bf16 v[66:69], v[158:161], v[222:225], v[66:69]
	s_setprio 0
	s_barrier
	s_mov_b32 m0, s51
	ds_read_b128 v[194:197], v192 offset:49152
	ds_read_b128 v[198:201], v192 offset:50176
	ds_read_b128 v[202:205], v192 offset:51200
	global_load_lds_dwordx4 v226, s[26:27]
	s_mov_b32 m0, s57
	ds_read_b128 v[222:225], v192 offset:56320
	global_load_lds_dwordx4 v227, s[26:27]
	s_mov_b32 m0, s84
	ds_read_b128 v[218:221], v192 offset:55296
	global_load_lds_dwordx4 v230, s[26:27]
	s_mov_b32 m0, s85
	ds_read_b128 v[214:217], v192 offset:54272
	global_load_lds_dwordx4 v231, s[26:27]
	s_mov_b32 m0, s68
	ds_read_b128 v[210:213], v192 offset:53248
	global_load_lds_dwordx4 v226, s[62:63]
	s_mov_b32 m0, s69
	ds_read_b128 v[206:209], v192 offset:52224
	global_load_lds_dwordx4 v227, s[62:63]
	s_waitcnt vmcnt(8)
	s_waitcnt lgkmcnt(0)
	s_barrier
	s_setprio 1
	s_waitcnt lgkmcnt(0)
	v_mfma_f32_16x16x32_bf16 v[62:65], v[130:133], v[194:197], v[62:65]
	v_mfma_f32_16x16x32_bf16 v[58:61], v[138:141], v[194:197], v[58:61]
	v_mfma_f32_16x16x32_bf16 v[54:57], v[130:133], v[202:205], v[54:57]
	v_mfma_f32_16x16x32_bf16 v[50:53], v[138:141], v[202:205], v[50:53]
	v_mfma_f32_16x16x32_bf16 v[46:49], v[130:133], v[210:213], v[46:49]
	v_mfma_f32_16x16x32_bf16 v[42:45], v[138:141], v[210:213], v[42:45]
	v_mfma_f32_16x16x32_bf16 v[38:41], v[130:133], v[218:221], v[38:41]
	v_mfma_f32_16x16x32_bf16 v[34:37], v[138:141], v[218:221], v[34:37]
	v_mfma_f32_16x16x32_bf16 v[62:65], v[134:137], v[198:201], v[62:65]
	v_mfma_f32_16x16x32_bf16 v[58:61], v[142:145], v[198:201], v[58:61]
	v_mfma_f32_16x16x32_bf16 v[54:57], v[134:137], v[206:209], v[54:57]
	v_mfma_f32_16x16x32_bf16 v[50:53], v[142:145], v[206:209], v[50:53]
	v_mfma_f32_16x16x32_bf16 v[46:49], v[134:137], v[214:217], v[46:49]
	v_mfma_f32_16x16x32_bf16 v[42:45], v[142:145], v[214:217], v[42:45]
	v_mfma_f32_16x16x32_bf16 v[38:41], v[134:137], v[222:225], v[38:41]
	v_mfma_f32_16x16x32_bf16 v[34:37], v[142:145], v[222:225], v[34:37]
	s_setprio 0
	s_setprio 1
	v_mfma_f32_16x16x32_bf16 v[30:33], v[146:149], v[194:197], v[30:33]
	v_mfma_f32_16x16x32_bf16 v[26:29], v[154:157], v[194:197], v[26:29]
	v_mfma_f32_16x16x32_bf16 v[22:25], v[146:149], v[202:205], v[22:25]
	v_mfma_f32_16x16x32_bf16 v[18:21], v[154:157], v[202:205], v[18:21]
	v_mfma_f32_16x16x32_bf16 v[14:17], v[146:149], v[210:213], v[14:17]
	v_mfma_f32_16x16x32_bf16 v[10:13], v[154:157], v[210:213], v[10:13]
	v_mfma_f32_16x16x32_bf16 v[6:9], v[146:149], v[218:221], v[6:9]
	v_mfma_f32_16x16x32_bf16 v[2:5], v[154:157], v[218:221], v[2:5]
	v_mfma_f32_16x16x32_bf16 v[30:33], v[150:153], v[198:201], v[30:33]
	v_mfma_f32_16x16x32_bf16 v[26:29], v[158:161], v[198:201], v[26:29]
	v_mfma_f32_16x16x32_bf16 v[22:25], v[150:153], v[206:209], v[22:25]
	v_mfma_f32_16x16x32_bf16 v[18:21], v[158:161], v[206:209], v[18:21]
	v_mfma_f32_16x16x32_bf16 v[14:17], v[150:153], v[214:217], v[14:17]
	v_mfma_f32_16x16x32_bf16 v[10:13], v[158:161], v[214:217], v[10:13]
	v_mfma_f32_16x16x32_bf16 v[6:9], v[150:153], v[222:225], v[6:9]
	v_mfma_f32_16x16x32_bf16 v[2:5], v[158:161], v[222:225], v[2:5]
	s_setprio 0
	s_barrier
; #define PG8_WAIT_V(n) asm volatile("s_waitcnt vmcnt(" #n ")" ::: "memory")
; #define PG8_WAIT_L(n) asm volatile("s_waitcnt lgkmcnt(" #n ")" ::: "memory")
; #define PG8_BAR __builtin_amdgcn_s_barrier()
; #define PG8_SCHED __builtin_amdgcn_sched_barrier(0)
; DI void gemm8_resid_epilogue(const GemmArgs& g, f32x4 (&acc)[2][2][4][2], const int brow, const int bcol, const int wr, const int wc, const int fr, const int fq) {
;     ...
;   auto base = [&](int ai, int bj) -> size_t { return (size_t)(brow + ai * 128 + wr * 64 + fr) * DM + bcol + bj * 128 + wc * 32 + fq * 4; };
;   f32x4 ra[4][2], rb[4][2];
;   auto ld = [&](f32x4 (&r)[4][2], size_t ib) {
; #pragma unroll
;     for (int m = 0; m < 4; ++m)
; #pragma unroll
;       for (int n = 0; n < 2; ++n) r[m][n] = *(const f32x4*)(src + ib + (size_t)(m * 16) * DM + n * 16);
;   };
;   auto st = [&](const f32x4 (&r)[4][2], const f32x4 (&a)[4][2], size_t ib) {
; #pragma unroll
;     for (int m = 0; m < 4; ++m)
; #pragma unroll
;       for (int n = 0; n < 2; ++n) {
;         f32x4 o;
;         o.x = r[m][n].x + sc * a[m][n][0]; o.y = r[m][n].y + sc * a[m][n][1];
;         o.z = r[m][n].z + sc * a[m][n][2]; o.w = r[m][n].w + sc * a[m][n][3];
;         *(f32x4*)(X + ib + (size_t)(m * 16) * DM + n * 16) = o;
;       }
;   };
;   const size_t b00 = base(0, 0), b01 = base(0, 1), b10 = base(1, 0), b11 = base(1, 1);
;   ld(ra, b00); ld(rb, b01);
;   st(ra, acc[0][0], b00); ld(ra, b10);
;   st(rb, acc[0][1], b01); ld(rb, b11);
;   st(ra, acc[1][0], b10);
; template <int EPI, bool ALIGN_EPI = true, bool SP2 = true>
; DI void gemm8_phase(const GemmArgs& g, char* lds_) {
;     ...
;         PG8_WAIT_V(8); PG8_WAIT_L(0); PG8_BAR; PG8_MMA(1, 0, At, B0); PG8_MMA(1, 1, At, B1); PG8_BAR; PG8_SCHED;
	s_add_u32 s48, s48, 0x100
	s_addc_u32 s49, s49, 0
	s_add_u32 vcc_lo, vcc_lo, 0x100
	s_addc_u32 vcc_hi, vcc_hi, 0
	s_cmp_ge_u32 s24, s50
	s_mov_b32 s62, s24
	s_cbranch_scc0 .LBB0_1055
	s_lshl_b32 s23, s23, 8
	s_add_i32 s23, s23, s21
	s_lshl_b32 s24, s91, 8
	v_or_b32_e32 v130, s23, v163
	v_ashrrev_i32_e32 v131, 31, v130
	s_ashr_i32 s25, s24, 31
	v_lshlrev_b64 v[130:131], 10, v[130:131]
	v_mov_b32_e32 v133, s25
	v_or_b32_e32 v132, s24, v166
	v_lshl_add_u64 v[130:131], v[130:131], 0, v[132:133]
	v_add_u32_e32 v134, s23, v193
	v_ashrrev_i32_e32 v135, 31, v134
	v_lshlrev_b64 v[226:227], 2, v[130:131]
	v_lshlrev_b64 v[134:135], 10, v[134:135]
	v_lshl_add_u64 v[130:131], s[40:41], 0, v[226:227]
	v_lshl_add_u64 v[172:173], v[134:135], 0, v[132:133]
	global_load_dwordx4 v[194:197], v[130:131], off
	global_load_dwordx4 v[198:201], v[130:131], off offset:64
	v_add_co_u32_e32 v132, vcc, s89, v130
	s_mov_b32 s23, s86
	s_nop 0
	v_addc_co_u32_e32 v133, vcc, 0, v131, vcc
	global_load_dwordx4 v[202:205], v[132:133], off
	global_load_dwordx4 v[206:209], v[132:133], off offset:64
	v_add_co_u32_e32 v134, vcc, s96, v130
	s_mov_b32 s91, s22
	s_nop 0
	v_addc_co_u32_e32 v135, vcc, 0, v131, vcc
	global_load_dwordx4 v[210:213], v[134:135], off
	global_load_dwordx4 v[214:217], v[134:135], off offset:64
	v_add_co_u32_e32 v228, vcc, s94, v130
	s_mov_b64 s[62:63], s[46:47]
	s_nop 0
	v_addc_co_u32_e32 v229, vcc, 0, v131, vcc
	global_load_dwordx4 v[218:221], v[228:229], off
	global_load_dwordx4 v[222:225], v[228:229], off offset:64
	global_load_dwordx4 v[158:161], v[130:131], off offset:512
	global_load_dwordx4 v[154:157], v[130:131], off offset:576
	global_load_dwordx4 v[150:153], v[132:133], off offset:512
	global_load_dwordx4 v[146:149], v[132:133], off offset:576
	global_load_dwordx4 v[142:145], v[134:135], off offset:512
	global_load_dwordx4 v[138:141], v[134:135], off offset:576
	s_nop 0
	global_load_dwordx4 v[134:137], v[228:229], off offset:512
	global_load_dwordx4 v[130:133], v[228:229], off offset:576
	s_mov_b64 s[48:49], s[44:45]
	s_waitcnt vmcnt(0)
	v_pk_fma_f32 v[194:195], s[0:1], v[126:127], v[194:195]
	v_lshl_add_u64 v[126:127], s[72:73], 0, v[226:227]
	v_pk_fma_f32 v[124:125], s[42:43], v[124:125], v[200:201]
	v_pk_fma_f32 v[122:123], s[0:1], v[122:123], v[198:199]
	global_store_dwordx4 v[126:127], v[122:125], off offset:64
	v_pk_fma_f32 v[196:197], s[42:43], v[128:129], v[196:197]
	global_store_dwordx4 v[126:127], v[194:197], off
	v_pk_fma_f32 v[122:123], s[42:43], v[120:121], v[204:205]
	v_pk_fma_f32 v[120:121], s[0:1], v[118:119], v[202:203]
	v_add_co_u32_e32 v118, vcc, s89, v126
	v_pk_fma_f32 v[116:117], s[42:43], v[116:117], v[208:209]
	s_nop 0
	v_addc_co_u32_e32 v119, vcc, 0, v127, vcc
	v_pk_fma_f32 v[114:115], s[0:1], v[114:115], v[206:207]
	global_store_dwordx4 v[118:119], v[114:117], off offset:64
	v_pk_fma_f32 v[108:109], s[42:43], v[108:109], v[216:217]
	v_pk_fma_f32 v[106:107], s[0:1], v[106:107], v[214:215]
	v_pk_fma_f32 v[114:115], s[42:43], v[112:113], v[212:213]
	v_pk_fma_f32 v[112:113], s[0:1], v[110:111], v[210:211]
	v_add_co_u32_e32 v110, vcc, s96, v126
	v_pk_fma_f32 v[100:101], s[42:43], v[100:101], v[224:225]
	s_nop 0
	v_addc_co_u32_e32 v111, vcc, 0, v127, vcc
	global_store_dwordx4 v[110:111], v[106:109], off offset:64
	v_pk_fma_f32 v[98:99], s[0:1], v[98:99], v[222:223]
	global_store_dwordx4 v[118:119], v[120:123], off
	v_pk_fma_f32 v[106:107], s[42:43], v[104:105], v[220:221]
	v_pk_fma_f32 v[104:105], s[0:1], v[102:103], v[218:219]
	v_add_co_u32_e32 v102, vcc, s94, v126
	v_lshlrev_b64 v[108:109], 2, v[172:173]
	s_nop 0
	v_addc_co_u32_e32 v103, vcc, 0, v127, vcc
	global_store_dwordx4 v[110:111], v[112:115], off
	global_store_dwordx4 v[102:103], v[104:107], off
	global_store_dwordx4 v[102:103], v[98:101], off offset:64
	v_lshl_add_u64 v[116:117], s[40:41], 0, v[108:109]
	global_load_dwordx4 v[104:107], v[116:117], off
	global_load_dwordx4 v[112:115], v[116:117], off offset:64
	v_add_co_u32_e32 v124, vcc, s89, v116
	v_pk_fma_f32 v[96:97], s[42:43], v[96:97], v[160:161]
	s_nop 0
	v_addc_co_u32_e32 v125, vcc, 0, v117, vcc
	global_load_dwordx4 v[120:123], v[124:125], off
	global_load_dwordx4 v[194:197], v[124:125], off offset:64
	v_add_co_u32_e32 v128, vcc, s96, v116
	v_pk_fma_f32 v[94:95], s[0:1], v[94:95], v[158:159]
	s_nop 0
	v_addc_co_u32_e32 v129, vcc, 0, v117, vcc
	global_load_dwordx4 v[198:201], v[128:129], off
	global_load_dwordx4 v[202:205], v[128:129], off offset:64
	v_add_co_u32_e32 v172, vcc, s94, v116
	v_pk_fma_f32 v[92:93], s[42:43], v[92:93], v[156:157]
	s_nop 0
	v_addc_co_u32_e32 v173, vcc, 0, v117, vcc
	v_pk_fma_f32 v[90:91], s[0:1], v[90:91], v[154:155]
	v_pk_fma_f32 v[88:89], s[42:43], v[88:89], v[152:153]
	v_pk_fma_f32 v[86:87], s[0:1], v[86:87], v[150:151]
	v_pk_fma_f32 v[84:85], s[42:43], v[84:85], v[148:149]
	v_pk_fma_f32 v[82:83], s[0:1], v[82:83], v[146:147]
	v_pk_fma_f32 v[80:81], s[42:43], v[80:81], v[144:145]
	v_pk_fma_f32 v[78:79], s[0:1], v[78:79], v[142:143]
	v_pk_fma_f32 v[76:77], s[42:43], v[76:77], v[140:141]
	v_pk_fma_f32 v[74:75], s[0:1], v[74:75], v[138:139]
	v_pk_fma_f32 v[72:73], s[42:43], v[72:73], v[136:137]
	v_pk_fma_f32 v[70:71], s[0:1], v[70:71], v[134:135]
	v_pk_fma_f32 v[68:69], s[42:43], v[68:69], v[132:133]
	v_pk_fma_f32 v[66:67], s[0:1], v[66:67], v[130:131]
	global_load_dwordx4 v[206:209], v[172:173], off
	global_load_dwordx4 v[98:101], v[172:173], off offset:64
	s_waitcnt vmcnt(7)
; DI void gemm8_resid_epilogue(const GemmArgs& g, f32x4 (&acc)[2][2][4][2], const int brow, const int bcol, const int wr, const int wc, const int fr, const int fq) {
;     ...
;   auto st = [&](const f32x4 (&r)[4][2], const f32x4 (&a)[4][2], size_t ib) {
; #pragma unroll
;     for (int m = 0; m < 4; ++m)
; #pragma unroll
;       for (int n = 0; n < 2; ++n) {
;         f32x4 o;
;         o.x = r[m][n].x + sc * a[m][n][0]; o.y = r[m][n].y + sc * a[m][n][1];
;         o.z = r[m][n].z + sc * a[m][n][2]; o.w = r[m][n].w + sc * a[m][n][3];
;         *(f32x4*)(X + ib + (size_t)(m * 16) * DM + n * 16) = o;
;       }
;   };
;   const size_t b00 = base(0, 0), b01 = base(0, 1), b10 = base(1, 0), b11 = base(1, 1);
;   ld(ra, b00); ld(rb, b01);
;   st(ra, acc[0][0], b00); ld(ra, b10);
;   st(rb, acc[0][1], b01); ld(rb, b11);
;   st(ra, acc[1][0], b10);
;   st(rb, acc[1][1], b11);
	v_pk_fma_f32 v[64:65], s[42:43], v[64:65], v[106:107]
	global_store_dwordx4 v[126:127], v[94:97], off offset:512
	global_store_dwordx4 v[126:127], v[90:93], off offset:576
	global_store_dwordx4 v[118:119], v[86:89], off offset:512
	global_store_dwordx4 v[118:119], v[82:85], off offset:576
	global_store_dwordx4 v[110:111], v[78:81], off offset:512
	global_store_dwordx4 v[110:111], v[74:77], off offset:576
	global_store_dwordx4 v[102:103], v[70:73], off offset:512
	global_store_dwordx4 v[102:103], v[66:69], off offset:576
	global_load_dwordx4 v[94:97], v[116:117], off offset:512
	global_load_dwordx4 v[90:93], v[116:117], off offset:576
	global_load_dwordx4 v[86:89], v[124:125], off offset:512
	global_load_dwordx4 v[82:85], v[124:125], off offset:576
	global_load_dwordx4 v[78:81], v[128:129], off offset:512
	global_load_dwordx4 v[74:77], v[128:129], off offset:576
	global_load_dwordx4 v[70:73], v[172:173], off offset:512
	global_load_dwordx4 v[66:69], v[172:173], off offset:576
	v_lshl_add_u64 v[102:103], s[72:73], 0, v[108:109]
	s_waitcnt vmcnt(22)
	v_pk_fma_f32 v[60:61], s[42:43], v[60:61], v[114:115]
	v_pk_fma_f32 v[58:59], s[0:1], v[58:59], v[112:113]
	global_store_dwordx4 v[102:103], v[58:61], off offset:64
	s_waitcnt vmcnt(21)
	v_pk_fma_f32 v[52:53], s[42:43], v[52:53], v[196:197]
	v_pk_fma_f32 v[50:51], s[0:1], v[50:51], v[194:195]
	v_add_co_u32_e32 v58, vcc, s89, v102
	s_waitcnt vmcnt(19)
	v_pk_fma_f32 v[44:45], s[42:43], v[44:45], v[204:205]
	v_addc_co_u32_e32 v59, vcc, 0, v103, vcc
	global_store_dwordx4 v[58:59], v[50:53], off offset:64
	v_pk_fma_f32 v[42:43], s[0:1], v[42:43], v[202:203]
	v_pk_fma_f32 v[62:63], s[0:1], v[62:63], v[104:105]
	v_add_co_u32_e32 v50, vcc, s96, v102
	v_pk_fma_f32 v[56:57], s[42:43], v[56:57], v[122:123]
	s_nop 0
	v_addc_co_u32_e32 v51, vcc, 0, v103, vcc
	global_store_dwordx4 v[50:51], v[42:45], off offset:64
	v_pk_fma_f32 v[54:55], s[0:1], v[54:55], v[120:121]
	v_pk_fma_f32 v[48:49], s[42:43], v[48:49], v[200:201]
	v_add_co_u32_e32 v42, vcc, s94, v102
	v_pk_fma_f32 v[46:47], s[0:1], v[46:47], v[198:199]
	s_nop 0
	v_addc_co_u32_e32 v43, vcc, 0, v103, vcc
	s_waitcnt vmcnt(20)
	v_pk_fma_f32 v[40:41], s[42:43], v[40:41], v[208:209]
	v_pk_fma_f32 v[38:39], s[0:1], v[38:39], v[206:207]
	s_waitcnt vmcnt(19)
	v_pk_fma_f32 v[36:37], s[42:43], v[36:37], v[100:101]
	v_pk_fma_f32 v[34:35], s[0:1], v[34:35], v[98:99]
	s_and_b64 vcc, exec, s[34:35]
	global_store_dwordx4 v[102:103], v[62:65], off
	global_store_dwordx4 v[58:59], v[54:57], off
	global_store_dwordx4 v[50:51], v[46:49], off
	global_store_dwordx4 v[42:43], v[38:41], off
	global_store_dwordx4 v[42:43], v[34:37], off offset:64
	s_waitcnt vmcnt(15)
	v_pk_fma_f32 v[32:33], s[42:43], v[32:33], v[96:97]
	v_pk_fma_f32 v[30:31], s[0:1], v[30:31], v[94:95]
	s_waitcnt vmcnt(14)
	v_pk_fma_f32 v[28:29], s[42:43], v[28:29], v[92:93]
	v_pk_fma_f32 v[26:27], s[0:1], v[26:27], v[90:91]
	s_waitcnt vmcnt(13)
	v_pk_fma_f32 v[24:25], s[42:43], v[24:25], v[88:89]
	v_pk_fma_f32 v[22:23], s[0:1], v[22:23], v[86:87]
	s_waitcnt vmcnt(12)
	v_pk_fma_f32 v[20:21], s[42:43], v[20:21], v[84:85]
	v_pk_fma_f32 v[18:19], s[0:1], v[18:19], v[82:83]
	s_waitcnt vmcnt(11)
	v_pk_fma_f32 v[16:17], s[42:43], v[16:17], v[80:81]
	v_pk_fma_f32 v[14:15], s[0:1], v[14:15], v[78:79]
	s_waitcnt vmcnt(10)
	v_pk_fma_f32 v[12:13], s[42:43], v[12:13], v[76:77]
	v_pk_fma_f32 v[10:11], s[0:1], v[10:11], v[74:75]
	s_waitcnt vmcnt(9)
	v_pk_fma_f32 v[8:9], s[42:43], v[8:9], v[72:73]
	v_pk_fma_f32 v[6:7], s[0:1], v[6:7], v[70:71]
	s_waitcnt vmcnt(8)
	v_pk_fma_f32 v[4:5], s[42:43], v[4:5], v[68:69]
	v_pk_fma_f32 v[2:3], s[0:1], v[2:3], v[66:67]
	global_store_dwordx4 v[102:103], v[30:33], off offset:512
	global_store_dwordx4 v[102:103], v[26:29], off offset:576
	global_store_dwordx4 v[58:59], v[22:25], off offset:512
	global_store_dwordx4 v[58:59], v[18:21], off offset:576
	global_store_dwordx4 v[50:51], v[14:17], off offset:512
	global_store_dwordx4 v[50:51], v[10:13], off offset:576
	global_store_dwordx4 v[42:43], v[6:9], off offset:512
	global_store_dwordx4 v[42:43], v[2:5], off offset:576
	s_cbranch_vccz .LBB0_1050
	s_waitcnt vmcnt(0)
	v_readlane_b32 s64, v254, 53
	v_readlane_b32 s66, v254, 55
	v_readlane_b32 s70, v254, 59
	v_readlane_b32 s24, v254, 51
	s_cmpk_gt_u32 s5, 0xff
	v_readlane_b32 s65, v254, 54
	v_readlane_b32 s67, v254, 56
	s_mov_b32 s55, s59
	v_readlane_b32 s71, v254, 60
	v_readlane_b32 s56, v254, 61
	v_readlane_b32 s79, v254, 62
	v_readlane_b32 s20, v254, 49
	v_readlane_b32 s21, v254, 50
	v_readlane_b32 s25, v254, 52
	s_cbranch_scc1 .LBB0_1059
	s_barrier
